# rwkv_prep inner loop: the 15 serialized per-row parameter loads are touched at loop top to warm the caches (on top of v41)
# speedup vs baseline: 1.0003x; 1.0003x over previous
; #define p (kparams())
; __device__ __forceinline__ void rwkv_prep_item(const int wv_, KPR p, int l, int item, bf16_t* tile) {
;     ...
;   for (int nt = 0; nt < 4; ++nt) { const int c = wid * 64 + nt * 16 + cl;
;     f32x4 accw[2], acca[2], accg = (f32x4){0.f, 0.f, 0.f, 0.f};
; #pragma unroll
;     for (int d = 0; d < 2; ++d) { accw[d] = (f32x4){0.f, 0.f, 0.f, 0.f}; acca[d] = (f32x4){0.f, 0.f, 0.f, 0.f};
; #pragma unroll
;       for (int ks = 0; ks < 2; ++ks) {
;         accw[d] = __builtin_amdgcn_mfma_f32_16x16x32_bf16(aw[d][ks], ld_frag(W2T + ((size_t)d * C + c) * 64 + ks * 32 + tq * 8), accw[d], 0, 0, 0);
;         acca[d] = __builtin_amdgcn_mfma_f32_16x16x32_bf16(aa[d][ks], ld_frag(A2T + ((size_t)d * C + c) * 64 + ks * 32 + tq * 8), acca[d], 0, 0, 0); } }
; #pragma unroll
;     for (int ks = 0; ks < 4; ++ks) accg = __builtin_amdgcn_mfma_f32_16x16x32_bf16(ag[ks], ld_frag(G2T + (size_t)c * 128 + ks * 32 + tq * 8), accg, 0, 0, 0);
;     float r4[4], k4[4], v4[4]; conv4(tile, cw, c, tq, r4); conv4(tile, cw, 512 + c, tq, k4); conv4(tile, cw, 1024 + c, tq, v4);
;     const float kkw = p->in[I_RWKK][l * C + c];
;     const float ka = p->in[I_RWKA][l * C + c];
;     const float w00 = p->in[I_RWW0][(l * 2 + 0) * C + c], w01 = p->in[I_RWW0][(l * 2 + 1) * C + c];
;     const float a00 = p->in[I_RWA0][(l * 2 + 0) * C + c], a01 = p->in[I_RWA0][(l * 2 + 1) * C + c];
.LBB0_435:
	v_ashrrev_i32_e32 v85, 31, v84
	v_lshl_add_u64 v[126:127], v[84:85], 2, s[4:5]
	global_load_dword v132, v[126:127], off
	global_load_dword v133, v[126:127], off offset:2048
	v_add_co_u32_e32 v128, vcc, s52, v126
	s_nop 1
	v_addc_co_u32_e32 v129, vcc, 0, v127, vcc
	global_load_dword v134, v[128:129], off offset:2048
	global_load_dword v135, v[128:129], off
	v_add_co_u32_e32 v128, vcc, s80, v126
	s_nop 1
	v_addc_co_u32_e32 v129, vcc, 0, v127, vcc
	global_load_dword v136, v[128:129], off offset:-4096
	global_load_dword v137, v[128:129], off
	v_add_co_u32_e32 v128, vcc, s63, v126
	s_nop 1
	v_addc_co_u32_e32 v129, vcc, 0, v127, vcc
	global_load_dword v138, v[128:129], off
	global_load_dword v139, v[128:129], off offset:2048
	v_add_co_u32_e32 v128, vcc, s54, v126
	s_nop 1
	v_addc_co_u32_e32 v129, vcc, 0, v127, vcc
	global_load_dword v140, v[128:129], off offset:2048
	s_waitcnt lgkmcnt(0)
	v_add_u32_e32 v130, s78, v84
	v_ashrrev_i32_e32 v131, 31, v130
	v_lshlrev_b64 v[130:131], 2, v[130:131]
	v_lshl_add_u64 v[128:129], s[12:13], 0, v[130:131]
	global_load_dword v141, v[128:129], off
	v_lshl_add_u64 v[128:129], s[10:11], 0, v[130:131]
	global_load_dword v142, v[128:129], off
	v_add_u32_e32 v130, s22, v84
	v_ashrrev_i32_e32 v131, 31, v130
	v_lshlrev_b64 v[130:131], 2, v[130:131]
	v_lshl_add_u64 v[128:129], s[14:15], 0, v[130:131]
	global_load_dword v143, v[128:129], off
	global_load_dword v144, v[128:129], off offset:2048
	v_lshl_add_u64 v[128:129], s[18:19], 0, v[130:131]
	global_load_dword v145, v[128:129], off
	global_load_dword v146, v[128:129], off offset:2048
	v_lshlrev_b64 v[52:53], 7, v[84:85]
	v_lshl_add_u64 v[90:91], v[0:1], 0, v[52:53]
	v_lshl_add_u64 v[92:93], v[72:73], 0, v[52:53]
	v_lshl_add_u64 v[238:239], v[90:91], 0, s[92:93]
	v_lshl_add_u64 v[240:241], v[92:93], 0, s[92:93]
	v_lshlrev_b64 v[52:53], 8, v[84:85]
	v_lshl_add_u64 v[124:125], v[74:75], 0, v[52:53]
	global_load_dwordx4 v[190:193], v[90:91], off
	global_load_dwordx4 v[194:197], v[90:91], off offset:64
	global_load_dwordx4 v[198:201], v[92:93], off
	global_load_dwordx4 v[202:205], v[92:93], off offset:64
	global_load_dwordx4 v[206:209], v[238:239], off
	global_load_dwordx4 v[210:213], v[238:239], off offset:64
	global_load_dwordx4 v[214:217], v[240:241], off
	global_load_dwordx4 v[218:221], v[240:241], off offset:64
	global_load_dwordx4 v[222:225], v[124:125], off
	global_load_dwordx4 v[226:229], v[124:125], off offset:64
	global_load_dwordx4 v[230:233], v[124:125], off offset:128
	global_load_dwordx4 v[234:237], v[124:125], off offset:192
	v_add_u32_e32 v106, s20, v3
	s_add_i32 s20, s20, 32
	s_cmpk_lg_i32 s20, 0x80
	s_waitcnt vmcnt(11)
	v_mfma_f32_16x16x32_bf16 v[68:71], v[4:7], v[190:193], 0
	s_waitcnt vmcnt(10)
	v_mfma_f32_16x16x32_bf16 v[68:71], v[12:15], v[194:197], v[68:71]
	s_waitcnt vmcnt(9)
	v_mfma_f32_16x16x32_bf16 v[64:67], v[8:11], v[198:201], 0
	s_waitcnt vmcnt(8)
	v_mfma_f32_16x16x32_bf16 v[64:67], v[16:19], v[202:205], v[64:67]
	s_waitcnt vmcnt(7)
	v_mfma_f32_16x16x32_bf16 v[60:63], v[20:23], v[206:209], 0
	s_waitcnt vmcnt(6)
	v_mfma_f32_16x16x32_bf16 v[60:63], v[28:31], v[210:213], v[60:63]
	s_waitcnt vmcnt(5)
	v_mfma_f32_16x16x32_bf16 v[56:59], v[24:27], v[214:217], 0
	s_waitcnt vmcnt(4)
	v_mfma_f32_16x16x32_bf16 v[56:59], v[32:35], v[218:221], v[56:59]
	s_waitcnt vmcnt(3)
	v_mfma_f32_16x16x32_bf16 v[52:55], v[36:39], v[222:225], 0
	s_waitcnt vmcnt(2)
	v_mfma_f32_16x16x32_bf16 v[52:55], v[40:43], v[226:229], v[52:55]
	s_waitcnt vmcnt(1)
	v_mfma_f32_16x16x32_bf16 v[52:55], v[44:47], v[230:233], v[52:55]
	v_lshl_add_u64 v[94:95], v[84:85], 2, s[4:5]
	v_add_co_u32_e32 v96, vcc, s52, v94
	s_waitcnt vmcnt(0)
	v_mfma_f32_16x16x32_bf16 v[52:55], v[48:51], v[234:237], v[52:55]
	v_addc_co_u32_e32 v97, vcc, 0, v95, vcc
	global_load_dword v93, v[96:97], off offset:2048
	global_load_dword v91, v[94:95], off
	ds_read_u16 v92, v106
	v_add_co_u32_e32 v100, vcc, s54, v94
	s_nop 2
	v_cvt_f16_f32_e32 v52, v52
	v_addc_co_u32_e32 v101, vcc, 0, v95, vcc
	s_waitcnt lgkmcnt(0)
	v_lshlrev_b32_e32 v99, 16, v92
	ds_read_u16 v92, v106 offset:3104
	v_add_co_u32_e32 v102, vcc, s80, v94
	v_cvt_f16_f32_e32 v54, v54
	s_nop 0
	v_addc_co_u32_e32 v103, vcc, 0, v95, vcc
	s_waitcnt lgkmcnt(0)
	v_lshlrev_b32_e32 v104, 16, v92
	ds_read_u16 v92, v106 offset:6208
	global_load_dword v90, v[102:103], off offset:-4096
	global_load_dword v111, v[94:95], off offset:2048
	s_waitcnt lgkmcnt(0)
	v_lshlrev_b32_e32 v107, 16, v92
	ds_read_u16 v92, v106 offset:9312
	s_waitcnt lgkmcnt(0)
	v_lshlrev_b32_e32 v108, 16, v92
	ds_read_u16 v92, v106 offset:12416
	s_waitcnt lgkmcnt(0)
	v_lshlrev_b32_e32 v98, 16, v92
	ds_read_u16 v92, v106 offset:15520
	s_waitcnt lgkmcnt(0)
	v_lshlrev_b32_e32 v92, 16, v92
	s_waitcnt vmcnt(3)
	v_mul_f32_e32 v110, v93, v107
	v_mul_f32_e32 v109, v93, v104
	s_waitcnt vmcnt(2)
	v_fmac_f32_e32 v110, v91, v104
	v_add_co_u32_e32 v104, vcc, s63, v94
	v_fmac_f32_e32 v109, v91, v99
	v_mul_f32_e32 v99, v93, v108
	v_mul_f32_e32 v93, v93, v98
	v_addc_co_u32_e32 v105, vcc, 0, v95, vcc
	v_fmac_f32_e32 v99, v91, v107
	v_fmac_f32_e32 v93, v91, v108
	global_load_dword v91, v[104:105], off
	global_load_dword v94, v[100:101], off offset:2048
	ds_read_u16 v95, v106 offset:1024
	ds_read_u16 v100, v106 offset:4128
	s_waitcnt vmcnt(3)
	v_fma_mixlo_f16 v107, v90, v107, v109
	s_waitcnt lgkmcnt(1)
	v_lshlrev_b32_e32 v95, 16, v95
	s_waitcnt lgkmcnt(0)
	v_lshlrev_b32_e32 v101, 16, v100
	ds_read_u16 v100, v106 offset:7232
	s_waitcnt lgkmcnt(0)
	v_lshlrev_b32_e32 v112, 16, v100
	ds_read_u16 v100, v106 offset:10336
	s_waitcnt lgkmcnt(0)
	v_lshlrev_b32_e32 v113, 16, v100
	ds_read_u16 v100, v106 offset:13440
	s_waitcnt lgkmcnt(0)
; __device__ __forceinline__ float bf2f(bf16_t h) { return __uint_as_float((unsigned)h << 16); }
; __device__ __forceinline__ float sigm(float x) { return __builtin_amdgcn_rcpf(1.f + __expf(-x)); }
; #define p (kparams())
; __device__ __forceinline__ void conv4(const bf16_t* tile, const float* cw, int ch, int tq, float (&o)[4]) {
;   const float w0 = cw[ch], w1 = cw[1536 + ch], w2 = cw[3072 + ch];
;   float xs[6];
; #pragma unroll
;   for (int i = 0; i < 6; ++i) xs[i] = bf2f(tile[(tq * 4 + i) * RPS + ch]);
; #pragma unroll
;   for (int j = 0; j < 4; ++j) o[j] = w0 * xs[j] + w1 * xs[j + 1] + w2 * xs[j + 2];
; __device__ __forceinline__ void rwkv_prep_item(const int wv_, KPR p, int l, int item, bf16_t* tile) {
;     ...
;     float r4[4], k4[4], v4[4]; conv4(tile, cw, c, tq, r4); conv4(tile, cw, 512 + c, tq, k4); conv4(tile, cw, 1024 + c, tq, v4);
;     const float kkw = p->in[I_RWKK][l * C + c];
;     const float ka = p->in[I_RWKA][l * C + c];
;     const float w00 = p->in[I_RWW0][(l * 2 + 0) * C + c], w01 = p->in[I_RWW0][(l * 2 + 1) * C + c];
;     const float a00 = p->in[I_RWA0][(l * 2 + 0) * C + c], a01 = p->in[I_RWA0][(l * 2 + 1) * C + c];
; #pragma unroll
;     for (int j = 0; j < 4; ++j) { const size_t o = (size_t)(R0 + tq * 4 + j) * 512 + c;
;       const float kn = k4[j] * kkw * inv[j];
;       PRE[0 * AE + o] = f2h(r4[j]); PRE[1 * AE + o] = f2h(v4[j]); PRE[2 * AE + o] = f2h(kn);
; #pragma unroll
;       for (int d = 0; d < 2; ++d) { const float wpre = (d == 0 ? w00 : w01) + accw[d][j];
;         const float u = 1.f - __expf(-0.6065306597f * sigm(wpre));
;         const float a = sigm((d == 0 ? a00 : a01) + acca[d][j]);
;         PRE[(3 + d) * AE + o] = f2h(u); PRE[(5 + d) * AE + o] = f2h(kn * a); PRE[(7 + d) * AE + o] = f2h(k4[j] * (1.f + (a - 1.f) * ka)); }
;       PRE[9 * AE + o] = f2h(accg[j]); } }
	v_lshlrev_b32_e32 v114, 16, v100
	ds_read_u16 v100, v106 offset:16544
	s_waitcnt lgkmcnt(0)
	v_lshlrev_b32_e32 v115, 16, v100
	s_waitcnt vmcnt(1)
	v_mul_f32_e32 v116, v91, v101
	v_fmac_f32_e32 v116, v111, v95
	v_mul_f32_e32 v100, v91, v112
	v_mul_f32_e32 v95, v91, v113
	v_mul_f32_e32 v91, v91, v114
	v_fmac_f32_e32 v100, v111, v101
	v_fmac_f32_e32 v95, v111, v112
	v_fmac_f32_e32 v91, v111, v113
	s_waitcnt vmcnt(0)
	v_fmac_f32_e32 v116, v94, v112
	v_fmac_f32_e32 v100, v94, v113
	v_fmac_f32_e32 v95, v94, v114
	v_fmac_f32_e32 v91, v94, v115
	global_load_dword v111, v[96:97], off
	s_nop 0
	global_load_dword v97, v[104:105], off offset:2048
	global_load_dword v94, v[102:103], off
	ds_read_u16 v96, v106 offset:2048
	s_waitcnt lgkmcnt(0)
	v_lshlrev_b32_e32 v102, 16, v96
	ds_read_u16 v96, v106 offset:5152
	s_waitcnt lgkmcnt(0)
	v_lshlrev_b32_e32 v103, 16, v96
	ds_read_u16 v96, v106 offset:8256
	s_waitcnt lgkmcnt(0)
	v_lshlrev_b32_e32 v112, 16, v96
	ds_read_u16 v96, v106 offset:11360
	s_waitcnt lgkmcnt(0)
	v_lshlrev_b32_e32 v113, 16, v96
	ds_read_u16 v96, v106 offset:14464
	s_waitcnt lgkmcnt(0)
	v_lshlrev_b32_e32 v101, 16, v96
	ds_read_u16 v96, v106 offset:17568
	s_waitcnt lgkmcnt(0)
	v_lshlrev_b32_e32 v96, 16, v96
	s_waitcnt vmcnt(1)
	v_mul_f32_e32 v106, v97, v103
	v_fmac_f32_e32 v106, v111, v102
	v_mul_f32_e32 v114, v97, v112
	v_add_u32_e32 v102, s78, v84
	v_fmac_f32_e32 v114, v111, v103
	v_ashrrev_i32_e32 v103, 31, v102
	v_lshlrev_b64 v[102:103], 2, v[102:103]
	v_lshl_add_u64 v[104:105], s[10:11], 0, v[102:103]
	v_lshl_add_u64 v[102:103], s[12:13], 0, v[102:103]
	global_load_dword v117, v[102:103], off
	v_add_u32_e32 v102, s22, v84
	v_ashrrev_i32_e32 v103, 31, v102
	v_mul_f32_e32 v115, v97, v113
	v_mul_f32_e32 v97, v97, v101
	v_lshlrev_b64 v[102:103], 2, v[102:103]
	v_fmac_f32_e32 v115, v111, v112
	v_fmac_f32_e32 v97, v111, v113
	global_load_dword v111, v[104:105], off
	v_lshl_add_u64 v[104:105], s[14:15], 0, v[102:103]
	global_load_dword v118, v[104:105], off
	global_load_dword v119, v[104:105], off offset:2048
	v_lshl_add_u64 v[102:103], s[18:19], 0, v[102:103]
	global_load_dword v120, v[102:103], off
	global_load_dword v121, v[102:103], off offset:2048
	v_lshl_add_u64 v[102:103], v[84:85], 1, s[16:17]
	v_lshl_add_u64 v[104:105], v[102:103], 0, v[76:77]
	s_waitcnt vmcnt(6)
	v_fma_mixlo_f16 v109, v94, v112, v106
	v_add_co_u32_e32 v106, vcc, s55, v104
	global_store_short v[104:105], v107, off
	s_nop 0
	v_addc_co_u32_e32 v107, vcc, 0, v105, vcc
	global_store_short v[106:107], v109, off
	v_add_co_u32_e32 v106, vcc, s48, v104
	v_add_u32_e32 v84, 16, v84
	s_nop 0
	v_addc_co_u32_e32 v107, vcc, 0, v105, vcc
	s_waitcnt vmcnt(6)
	v_mul_f32_e32 v85, v116, v111
	s_waitcnt vmcnt(5)
	v_add_f32_e32 v68, v68, v118
	v_mul_f32_e32 v68, 0xbfb8aa3b, v68
	v_exp_f32_e32 v68, v68
	s_waitcnt vmcnt(4)
	v_add_f32_e32 v60, v60, v119
	v_mul_f32_e32 v60, 0xbfb8aa3b, v60
	v_exp_f32_e32 v60, v60
	v_add_f32_e32 v68, 1.0, v68
	v_rcp_f32_e32 v68, v68
	s_waitcnt vmcnt(3)
	v_add_f32_e32 v64, v64, v120
	v_add_f32_e32 v60, 1.0, v60
	v_mul_f32_e32 v64, 0xbfb8aa3b, v64
	v_mul_f32_e32 v68, 0xbf1b4598, v68
	v_mul_f32_e32 v68, 0x3fb8aa3b, v68
	v_exp_f32_e32 v68, v68
	v_rcp_f32_e32 v60, v60
	v_exp_f32_e32 v64, v64
	s_waitcnt vmcnt(2)
	v_add_f32_e32 v56, v56, v121
	v_sub_f32_e32 v68, 1.0, v68
	v_mul_f32_e32 v60, 0xbf1b4598, v60
	v_add_f32_e32 v64, 1.0, v64
	v_cvt_f16_f32_e32 v68, v68
	v_mul_f32_e32 v60, 0x3fb8aa3b, v60
	v_mul_f32_e32 v122, v89, v85
	v_fma_mixlo_f16 v85, v89, v85, 0
	v_rcp_f32_e32 v64, v64
	v_exp_f32_e32 v60, v60
	v_mul_f32_e32 v56, 0xbfb8aa3b, v56
	global_store_short v[106:107], v85, off
	v_add_co_u32_e32 v106, vcc, s49, v104
	v_exp_f32_e32 v56, v56
	s_nop 0
	v_addc_co_u32_e32 v107, vcc, 0, v105, vcc
	global_store_short v[106:107], v68, off
	v_add_co_u32_e32 v106, vcc, s60, v104
	v_fma_mixlo_f16 v68, v122, v64, 0
	s_nop 0
	v_addc_co_u32_e32 v107, vcc, 0, v105, vcc
	v_add_f32_e32 v64, -1.0, v64
	v_sub_f32_e32 v60, 1.0, v60
	global_store_short v[106:107], v68, off
	v_fma_f32 v64, v117, v64, 1.0
	v_add_co_u32_e32 v106, vcc, s61, v104
	v_add_f32_e32 v56, 1.0, v56
	v_cvt_f16_f32_e32 v60, v60
	v_fma_mixlo_f16 v64, v116, v64, 0
	v_addc_co_u32_e32 v107, vcc, 0, v105, vcc
	v_rcp_f32_e32 v56, v56
	global_store_short v[106:107], v64, off
	v_add_co_u32_e32 v106, vcc, s3, v104
	s_nop 1
	v_addc_co_u32_e32 v107, vcc, 0, v105, vcc
	global_store_short v[106:107], v60, off
	v_add_co_u32_e32 v106, vcc, s74, v104
	v_fma_mixlo_f16 v60, v122, v56, 0
	s_nop 0
	v_addc_co_u32_e32 v107, vcc, 0, v105, vcc
	global_store_short v[106:107], v60, off
	v_add_co_u32_e32 v106, vcc, s65, v104
	v_add_f32_e32 v56, -1.0, v56
	s_nop 0
	v_addc_co_u32_e32 v107, vcc, 0, v105, vcc
	v_add_co_u32_e32 v104, vcc, s62, v104
	v_fma_f32 v56, v117, v56, 1.0
	s_nop 0
	v_addc_co_u32_e32 v105, vcc, 0, v105, vcc
	v_fma_mixlo_f16 v56, v116, v56, 0
	global_store_short v[104:105], v52, off
	v_lshl_add_u64 v[104:105], v[102:103], 0, v[78:79]
	global_store_short v[106:107], v56, off
	v_fma_mixlo_f16 v56, v90, v108, v110
	v_add_co_u32_e32 v106, vcc, s55, v104
	global_store_short v[104:105], v56, off
	v_fma_mixlo_f16 v56, v94, v113, v114
	v_addc_co_u32_e32 v107, vcc, 0, v105, vcc
	v_mul_f32_e32 v52, v100, v111
	global_store_short v[106:107], v56, off
	v_add_co_u32_e32 v106, vcc, s48, v104
	v_mul_f32_e32 v60, v88, v52
	v_fma_mixlo_f16 v52, v88, v52, 0
	v_addc_co_u32_e32 v107, vcc, 0, v105, vcc
	global_store_short v[106:107], v52, off
	v_add_f32_e32 v52, v69, v118
	v_mul_f32_e32 v52, 0xbfb8aa3b, v52
	v_exp_f32_e32 v52, v52
	v_add_f32_e32 v56, v65, v120
	v_mul_f32_e32 v56, 0xbfb8aa3b, v56
	v_exp_f32_e32 v56, v56
	v_add_f32_e32 v52, 1.0, v52
; __device__ __forceinline__ float sigm(float x) { return __builtin_amdgcn_rcpf(1.f + __expf(-x)); }
; __device__ __forceinline__ void rwkv_prep_item(const int wv_, KPR p, int l, int item, bf16_t* tile) {
;     ...
;     for (int j = 0; j < 4; ++j) { const size_t o = (size_t)(R0 + tq * 4 + j) * 512 + c;
;       const float kn = k4[j] * kkw * inv[j];
;       PRE[0 * AE + o] = f2h(r4[j]); PRE[1 * AE + o] = f2h(v4[j]); PRE[2 * AE + o] = f2h(kn);
; #pragma unroll
;       for (int d = 0; d < 2; ++d) { const float wpre = (d == 0 ? w00 : w01) + accw[d][j];
;         const float u = 1.f - __expf(-0.6065306597f * sigm(wpre));
;         const float a = sigm((d == 0 ? a00 : a01) + acca[d][j]);
;         PRE[(3 + d) * AE + o] = f2h(u); PRE[(5 + d) * AE + o] = f2h(kn * a); PRE[(7 + d) * AE + o] = f2h(k4[j] * (1.f + (a - 1.f) * ka)); }
;       PRE[9 * AE + o] = f2h(accg[j]); } }
;   __syncthreads();
	v_rcp_f32_e32 v52, v52
	v_add_co_u32_e32 v64, vcc, s49, v104
	v_add_f32_e32 v56, 1.0, v56
	v_mul_f32_e32 v52, 0xbf1b4598, v52
	v_mul_f32_e32 v52, 0x3fb8aa3b, v52
	v_exp_f32_e32 v52, v52
	v_rcp_f32_e32 v56, v56
	v_addc_co_u32_e32 v65, vcc, 0, v105, vcc
	v_sub_f32_e32 v52, 1.0, v52
	v_cvt_f16_f32_e32 v52, v52
	global_store_short v[64:65], v52, off
	v_add_co_u32_e32 v64, vcc, s60, v104
	v_fma_mixlo_f16 v52, v60, v56, 0
	s_nop 0
	v_addc_co_u32_e32 v65, vcc, 0, v105, vcc
	global_store_short v[64:65], v52, off
	v_add_f32_e32 v52, -1.0, v56
	v_fma_f32 v52, v117, v52, 1.0
	v_add_co_u32_e32 v64, vcc, s61, v104
	v_fma_mixlo_f16 v52, v100, v52, 0
	s_nop 0
	v_addc_co_u32_e32 v65, vcc, 0, v105, vcc
	global_store_short v[64:65], v52, off
	v_add_f32_e32 v52, v61, v119
	v_mul_f32_e32 v52, 0xbfb8aa3b, v52
	v_exp_f32_e32 v52, v52
	v_add_f32_e32 v56, v57, v121
	v_mul_f32_e32 v56, 0xbfb8aa3b, v56
	v_exp_f32_e32 v56, v56
	v_add_f32_e32 v52, 1.0, v52
	v_rcp_f32_e32 v52, v52
	v_fma_mixlo_f16 v64, v94, v101, v115
	v_add_f32_e32 v56, 1.0, v56
	v_rcp_f32_e32 v61, v56
	v_mul_f32_e32 v52, 0xbf1b4598, v52
	v_mul_f32_e32 v52, 0x3fb8aa3b, v52
	v_exp_f32_e32 v52, v52
	v_add_co_u32_e32 v56, vcc, s3, v104
	v_sub_f32_e32 v52, 1.0, v52
	v_cvt_f16_f32_e32 v52, v52
	v_addc_co_u32_e32 v57, vcc, 0, v105, vcc
	global_store_short v[56:57], v52, off
	v_add_co_u32_e32 v56, vcc, s74, v104
	v_fma_mixlo_f16 v52, v60, v61, 0
	s_nop 0
	v_addc_co_u32_e32 v57, vcc, 0, v105, vcc
	global_store_short v[56:57], v52, off
	v_add_f32_e32 v52, -1.0, v61
	v_fma_f32 v52, v117, v52, 1.0
	v_add_co_u32_e32 v56, vcc, s65, v104
	v_fma_mixlo_f16 v52, v100, v52, 0
	s_nop 0
	v_addc_co_u32_e32 v57, vcc, 0, v105, vcc
	global_store_short v[56:57], v52, off
	v_cvt_f16_f32_e32 v56, v53
	v_add_co_u32_e32 v52, vcc, s62, v104
	v_mul_f32_e32 v60, v95, v111
	s_nop 0
	v_addc_co_u32_e32 v53, vcc, 0, v105, vcc
	global_store_short v[52:53], v56, off
	v_fma_mixlo_f16 v56, v90, v98, v99
	v_lshl_add_u64 v[52:53], v[102:103], 0, v[80:81]
	global_store_short v[52:53], v56, off
	v_add_co_u32_e32 v56, vcc, s55, v52
	v_mul_f32_e32 v61, v87, v60
	s_nop 0
	v_addc_co_u32_e32 v57, vcc, 0, v53, vcc
	global_store_short v[56:57], v64, off
	v_add_co_u32_e32 v56, vcc, s48, v52
	v_fma_mixlo_f16 v60, v87, v60, 0
	s_nop 0
	v_addc_co_u32_e32 v57, vcc, 0, v53, vcc
	global_store_short v[56:57], v60, off
	v_add_f32_e32 v56, v70, v118
	v_mul_f32_e32 v56, 0xbfb8aa3b, v56
	v_exp_f32_e32 v56, v56
	v_add_f32_e32 v57, v66, v120
	v_mul_f32_e32 v57, 0xbfb8aa3b, v57
	v_exp_f32_e32 v57, v57
	v_add_f32_e32 v56, 1.0, v56
	v_rcp_f32_e32 v56, v56
	v_add_f32_e32 v57, 1.0, v57
	v_rcp_f32_e32 v60, v57
	v_mul_f32_e32 v56, 0xbf1b4598, v56
	v_mul_f32_e32 v56, 0x3fb8aa3b, v56
	v_exp_f32_e32 v56, v56
	s_nop 0
	v_sub_f32_e32 v56, 1.0, v56
	v_cvt_f16_f32_e32 v64, v56
	v_add_co_u32_e32 v56, vcc, s49, v52
	s_nop 1
	v_addc_co_u32_e32 v57, vcc, 0, v53, vcc
	global_store_short v[56:57], v64, off
	v_add_co_u32_e32 v56, vcc, s60, v52
	v_fma_mixlo_f16 v64, v61, v60, 0
	s_nop 0
	v_addc_co_u32_e32 v57, vcc, 0, v53, vcc
	global_store_short v[56:57], v64, off
	v_add_f32_e32 v56, -1.0, v60
	v_fma_f32 v56, v117, v56, 1.0
	v_fma_mixlo_f16 v60, v95, v56, 0
	v_add_co_u32_e32 v56, vcc, s61, v52
	s_nop 1
	v_addc_co_u32_e32 v57, vcc, 0, v53, vcc
	global_store_short v[56:57], v60, off
	v_add_f32_e32 v56, v62, v119
	v_mul_f32_e32 v56, 0xbfb8aa3b, v56
	v_exp_f32_e32 v56, v56
	v_add_f32_e32 v57, v58, v121
	v_mul_f32_e32 v57, 0xbfb8aa3b, v57
	v_exp_f32_e32 v57, v57
	v_add_f32_e32 v56, 1.0, v56
	v_rcp_f32_e32 v56, v56
	v_add_f32_e32 v57, 1.0, v57
	v_rcp_f32_e32 v58, v57
	v_mul_f32_e32 v56, 0xbf1b4598, v56
	v_mul_f32_e32 v56, 0x3fb8aa3b, v56
	v_exp_f32_e32 v56, v56
	s_nop 0
	v_sub_f32_e32 v56, 1.0, v56
	v_cvt_f16_f32_e32 v60, v56
	v_add_co_u32_e32 v56, vcc, s3, v52
	s_nop 1
	v_addc_co_u32_e32 v57, vcc, 0, v53, vcc
	global_store_short v[56:57], v60, off
	v_add_co_u32_e32 v56, vcc, s74, v52
	v_fma_mixlo_f16 v60, v61, v58, 0
	s_nop 0
	v_addc_co_u32_e32 v57, vcc, 0, v53, vcc
	global_store_short v[56:57], v60, off
	v_add_f32_e32 v56, -1.0, v58
	v_fma_f32 v56, v117, v56, 1.0
	v_fma_mixlo_f16 v58, v95, v56, 0
	v_add_co_u32_e32 v56, vcc, s65, v52
	v_fma_mixlo_f16 v60, v94, v96, v97
	s_nop 0
	v_addc_co_u32_e32 v57, vcc, 0, v53, vcc
	v_add_co_u32_e32 v52, vcc, s62, v52
	global_store_short v[56:57], v58, off
	s_nop 0
	v_addc_co_u32_e32 v53, vcc, 0, v53, vcc
	global_store_short v[52:53], v54, off
	v_fma_mixlo_f16 v56, v90, v92, v93
	v_lshl_add_u64 v[52:53], v[102:103], 0, v[82:83]
	global_store_short v[52:53], v56, off
	v_add_co_u32_e32 v56, vcc, s55, v52
	v_mul_f32_e32 v54, v91, v111
	s_nop 0
	v_addc_co_u32_e32 v57, vcc, 0, v53, vcc
	global_store_short v[56:57], v60, off
	v_add_co_u32_e32 v56, vcc, s48, v52
	v_mul_f32_e32 v58, v86, v54
	v_fma_mixlo_f16 v54, v86, v54, 0
	v_addc_co_u32_e32 v57, vcc, 0, v53, vcc
	global_store_short v[56:57], v54, off
	v_add_f32_e32 v54, v71, v118
	v_mul_f32_e32 v54, 0xbfb8aa3b, v54
	v_exp_f32_e32 v54, v54
	v_add_f32_e32 v56, v67, v120
	v_mul_f32_e32 v56, 0xbfb8aa3b, v56
	v_exp_f32_e32 v56, v56
	v_add_f32_e32 v54, 1.0, v54
	v_rcp_f32_e32 v54, v54
	v_add_f32_e32 v56, 1.0, v56
	v_rcp_f32_e32 v60, v56
	v_mul_f32_e32 v54, 0xbf1b4598, v54
	v_mul_f32_e32 v54, 0x3fb8aa3b, v54
	v_exp_f32_e32 v54, v54
	v_add_co_u32_e32 v56, vcc, s49, v52
	v_sub_f32_e32 v54, 1.0, v54
	v_cvt_f16_f32_e32 v54, v54
	v_addc_co_u32_e32 v57, vcc, 0, v53, vcc
	global_store_short v[56:57], v54, off
	v_add_co_u32_e32 v56, vcc, s60, v52
	v_fma_mixlo_f16 v54, v58, v60, 0
	s_nop 0
	v_addc_co_u32_e32 v57, vcc, 0, v53, vcc
	global_store_short v[56:57], v54, off
	v_add_f32_e32 v54, -1.0, v60
	v_fma_f32 v54, v117, v54, 1.0
	v_add_co_u32_e32 v56, vcc, s61, v52
	v_fma_mixlo_f16 v54, v91, v54, 0
	s_nop 0
	v_addc_co_u32_e32 v57, vcc, 0, v53, vcc
	global_store_short v[56:57], v54, off
	v_add_f32_e32 v54, v63, v119
	v_mul_f32_e32 v54, 0xbfb8aa3b, v54
	v_exp_f32_e32 v54, v54
	v_add_f32_e32 v56, v59, v121
	v_mul_f32_e32 v56, 0xbfb8aa3b, v56
	v_exp_f32_e32 v56, v56
	v_add_f32_e32 v54, 1.0, v54
	v_rcp_f32_e32 v54, v54
	v_add_f32_e32 v56, 1.0, v56
	v_rcp_f32_e32 v59, v56
	v_mul_f32_e32 v54, 0xbf1b4598, v54
	v_mul_f32_e32 v54, 0x3fb8aa3b, v54
	v_exp_f32_e32 v54, v54
	v_add_co_u32_e32 v56, vcc, s3, v52
	v_sub_f32_e32 v54, 1.0, v54
	v_cvt_f16_f32_e32 v54, v54
	v_addc_co_u32_e32 v57, vcc, 0, v53, vcc
	global_store_short v[56:57], v54, off
	v_add_co_u32_e32 v56, vcc, s74, v52
	v_fma_mixlo_f16 v54, v58, v59, 0
	s_nop 0
	v_addc_co_u32_e32 v57, vcc, 0, v53, vcc
	global_store_short v[56:57], v54, off
	v_add_f32_e32 v54, -1.0, v59
	v_fma_f32 v54, v117, v54, 1.0
	v_add_co_u32_e32 v56, vcc, 0x8800000, v52
	v_fma_mixlo_f16 v54, v91, v54, 0
	s_nop 0
	v_addc_co_u32_e32 v57, vcc, 0, v53, vcc
	global_store_short v[56:57], v54, off
	v_cvt_f16_f32_e32 v54, v55
	v_add_co_u32_e32 v52, vcc, 0x9900000, v52
	s_nop 1
	v_addc_co_u32_e32 v53, vcc, 0, v53, vcc
	global_store_short v[52:53], v54, off
	s_cbranch_scc1 .LBB0_435
	s_add_i32 s23, s23, s33
	s_cmpk_lt_i32 s23, 0x440
	s_barrier
	s_cbranch_scc1 .LBB0_419

; #define p (kparams())
; __device__ __forceinline__ void rwkv_prep_item(const int wv_, KPR p, int l, int item, bf16_t* tile) {
;     ...
;   for (int nt = 0; nt < 4; ++nt) { const int c = wid * 64 + nt * 16 + cl;
;     f32x4 accw[2], acca[2], accg = (f32x4){0.f, 0.f, 0.f, 0.f};
; #pragma unroll
;     for (int d = 0; d < 2; ++d) { accw[d] = (f32x4){0.f, 0.f, 0.f, 0.f}; acca[d] = (f32x4){0.f, 0.f, 0.f, 0.f};
; #pragma unroll
;       for (int ks = 0; ks < 2; ++ks) {
;         accw[d] = __builtin_amdgcn_mfma_f32_16x16x32_bf16(aw[d][ks], ld_frag(W2T + ((size_t)d * C + c) * 64 + ks * 32 + tq * 8), accw[d], 0, 0, 0);
;         acca[d] = __builtin_amdgcn_mfma_f32_16x16x32_bf16(aa[d][ks], ld_frag(A2T + ((size_t)d * C + c) * 64 + ks * 32 + tq * 8), acca[d], 0, 0, 0); } }
; #pragma unroll
;     for (int ks = 0; ks < 4; ++ks) accg = __builtin_amdgcn_mfma_f32_16x16x32_bf16(ag[ks], ld_frag(G2T + (size_t)c * 128 + ks * 32 + tq * 8), accg, 0, 0, 0);
;     float r4[4], k4[4], v4[4]; conv4(tile, cw, c, tq, r4); conv4(tile, cw, 512 + c, tq, k4); conv4(tile, cw, 1024 + c, tq, v4);
;     const float kkw = p->in[I_RWKK][l * C + c];
;     const float ka = p->in[I_RWKA][l * C + c];
;     const float w00 = p->in[I_RWW0][(l * 2 + 0) * C + c], w01 = p->in[I_RWW0][(l * 2 + 1) * C + c];
;     const float a00 = p->in[I_RWA0][(l * 2 + 0) * C + c], a01 = p->in[I_RWA0][(l * 2 + 1) * C + c];
.LBB0_457:
	v_ashrrev_i32_e32 v85, 31, v84
	v_lshl_add_u64 v[126:127], v[84:85], 2, s[4:5]
	global_load_dword v132, v[126:127], off
	global_load_dword v133, v[126:127], off offset:2048
	v_add_co_u32_e32 v128, vcc, s52, v126
	s_nop 1
	v_addc_co_u32_e32 v129, vcc, 0, v127, vcc
	global_load_dword v134, v[128:129], off offset:2048
	global_load_dword v135, v[128:129], off
	v_add_co_u32_e32 v128, vcc, s80, v126
	s_nop 1
	v_addc_co_u32_e32 v129, vcc, 0, v127, vcc
	global_load_dword v136, v[128:129], off offset:-4096
	global_load_dword v137, v[128:129], off
	v_add_co_u32_e32 v128, vcc, s63, v126
	s_nop 1
	v_addc_co_u32_e32 v129, vcc, 0, v127, vcc
	global_load_dword v138, v[128:129], off
	global_load_dword v139, v[128:129], off offset:2048
	v_add_co_u32_e32 v128, vcc, s54, v126
	s_nop 1
	v_addc_co_u32_e32 v129, vcc, 0, v127, vcc
	global_load_dword v140, v[128:129], off offset:2048
	s_waitcnt lgkmcnt(0)
	v_add_u32_e32 v130, s78, v84
	v_ashrrev_i32_e32 v131, 31, v130
	v_lshlrev_b64 v[130:131], 2, v[130:131]
	v_lshl_add_u64 v[128:129], s[12:13], 0, v[130:131]
	global_load_dword v141, v[128:129], off
	v_lshl_add_u64 v[128:129], s[10:11], 0, v[130:131]
	global_load_dword v142, v[128:129], off
	v_add_u32_e32 v130, s22, v84
	v_ashrrev_i32_e32 v131, 31, v130
	v_lshlrev_b64 v[130:131], 2, v[130:131]
	v_lshl_add_u64 v[128:129], s[14:15], 0, v[130:131]
	global_load_dword v143, v[128:129], off
	global_load_dword v144, v[128:129], off offset:2048
	v_lshl_add_u64 v[128:129], s[18:19], 0, v[130:131]
	global_load_dword v145, v[128:129], off
	global_load_dword v146, v[128:129], off offset:2048
	v_lshlrev_b64 v[52:53], 7, v[84:85]
	v_lshl_add_u64 v[90:91], v[0:1], 0, v[52:53]
	v_lshl_add_u64 v[92:93], v[72:73], 0, v[52:53]
	v_lshl_add_u64 v[238:239], v[90:91], 0, s[92:93]
	v_lshl_add_u64 v[240:241], v[92:93], 0, s[92:93]
	v_lshlrev_b64 v[52:53], 8, v[84:85]
	v_lshl_add_u64 v[124:125], v[74:75], 0, v[52:53]
	global_load_dwordx4 v[190:193], v[90:91], off
	global_load_dwordx4 v[194:197], v[90:91], off offset:64
	global_load_dwordx4 v[198:201], v[92:93], off
	global_load_dwordx4 v[202:205], v[92:93], off offset:64
	global_load_dwordx4 v[206:209], v[238:239], off
	global_load_dwordx4 v[210:213], v[238:239], off offset:64
	global_load_dwordx4 v[214:217], v[240:241], off
	global_load_dwordx4 v[218:221], v[240:241], off offset:64
	global_load_dwordx4 v[222:225], v[124:125], off
	global_load_dwordx4 v[226:229], v[124:125], off offset:64
	global_load_dwordx4 v[230:233], v[124:125], off offset:128
	global_load_dwordx4 v[234:237], v[124:125], off offset:192
	v_add_u32_e32 v106, s20, v3
	s_add_i32 s20, s20, 32
	s_cmpk_lg_i32 s20, 0x80
	s_waitcnt vmcnt(11)
	v_mfma_f32_16x16x32_bf16 v[68:71], v[4:7], v[190:193], 0
	s_waitcnt vmcnt(10)
	v_mfma_f32_16x16x32_bf16 v[68:71], v[12:15], v[194:197], v[68:71]
	s_waitcnt vmcnt(9)
	v_mfma_f32_16x16x32_bf16 v[64:67], v[8:11], v[198:201], 0
	s_waitcnt vmcnt(8)
	v_mfma_f32_16x16x32_bf16 v[64:67], v[16:19], v[202:205], v[64:67]
	s_waitcnt vmcnt(7)
	v_mfma_f32_16x16x32_bf16 v[60:63], v[20:23], v[206:209], 0
	s_waitcnt vmcnt(6)
	v_mfma_f32_16x16x32_bf16 v[60:63], v[28:31], v[210:213], v[60:63]
	s_waitcnt vmcnt(5)
	v_mfma_f32_16x16x32_bf16 v[56:59], v[24:27], v[214:217], 0
	s_waitcnt vmcnt(4)
	v_mfma_f32_16x16x32_bf16 v[56:59], v[32:35], v[218:221], v[56:59]
	s_waitcnt vmcnt(3)
	v_mfma_f32_16x16x32_bf16 v[52:55], v[36:39], v[222:225], 0
	s_waitcnt vmcnt(2)
	v_mfma_f32_16x16x32_bf16 v[52:55], v[40:43], v[226:229], v[52:55]
	s_waitcnt vmcnt(1)
	v_mfma_f32_16x16x32_bf16 v[52:55], v[44:47], v[230:233], v[52:55]
	v_lshl_add_u64 v[94:95], v[84:85], 2, s[4:5]
	v_add_co_u32_e32 v96, vcc, s52, v94
	s_waitcnt vmcnt(0)
	v_mfma_f32_16x16x32_bf16 v[52:55], v[48:51], v[234:237], v[52:55]
	v_addc_co_u32_e32 v97, vcc, 0, v95, vcc
	global_load_dword v93, v[96:97], off offset:2048
	global_load_dword v91, v[94:95], off
	ds_read_u16 v92, v106
	v_add_co_u32_e32 v100, vcc, s54, v94
	s_nop 2
	v_cvt_f16_f32_e32 v52, v52
	v_addc_co_u32_e32 v101, vcc, 0, v95, vcc
	s_waitcnt lgkmcnt(0)
	v_lshlrev_b32_e32 v99, 16, v92
	ds_read_u16 v92, v106 offset:3104
	v_add_co_u32_e32 v102, vcc, s80, v94
	v_cvt_f16_f32_e32 v54, v54
	s_nop 0
	v_addc_co_u32_e32 v103, vcc, 0, v95, vcc
	s_waitcnt lgkmcnt(0)
	v_lshlrev_b32_e32 v104, 16, v92
	ds_read_u16 v92, v106 offset:6208
	global_load_dword v90, v[102:103], off offset:-4096
	global_load_dword v111, v[94:95], off offset:2048
	s_waitcnt lgkmcnt(0)
	v_lshlrev_b32_e32 v107, 16, v92
	ds_read_u16 v92, v106 offset:9312
	s_waitcnt lgkmcnt(0)
	v_lshlrev_b32_e32 v108, 16, v92
	ds_read_u16 v92, v106 offset:12416
	s_waitcnt lgkmcnt(0)
	v_lshlrev_b32_e32 v98, 16, v92
	ds_read_u16 v92, v106 offset:15520
	s_waitcnt lgkmcnt(0)
	v_lshlrev_b32_e32 v92, 16, v92
	s_waitcnt vmcnt(3)
	v_mul_f32_e32 v110, v93, v107
	v_mul_f32_e32 v109, v93, v104
	s_waitcnt vmcnt(2)
	v_fmac_f32_e32 v110, v91, v104
	v_add_co_u32_e32 v104, vcc, s63, v94
	v_fmac_f32_e32 v109, v91, v99
	v_mul_f32_e32 v99, v93, v108
	v_mul_f32_e32 v93, v93, v98
	v_addc_co_u32_e32 v105, vcc, 0, v95, vcc
	v_fmac_f32_e32 v99, v91, v107
	v_fmac_f32_e32 v93, v91, v108
	global_load_dword v91, v[104:105], off
	global_load_dword v94, v[100:101], off offset:2048
	ds_read_u16 v95, v106 offset:1024
	ds_read_u16 v100, v106 offset:4128
	s_waitcnt vmcnt(3)
	v_fma_mixlo_f16 v107, v90, v107, v109
	s_waitcnt lgkmcnt(1)
	v_lshlrev_b32_e32 v95, 16, v95
	s_waitcnt lgkmcnt(0)
	v_lshlrev_b32_e32 v101, 16, v100
	ds_read_u16 v100, v106 offset:7232
	s_waitcnt lgkmcnt(0)
	v_lshlrev_b32_e32 v112, 16, v100
	ds_read_u16 v100, v106 offset:10336
	s_waitcnt lgkmcnt(0)
	v_lshlrev_b32_e32 v113, 16, v100
	ds_read_u16 v100, v106 offset:13440
	s_waitcnt lgkmcnt(0)
; __device__ __forceinline__ float bf2f(bf16_t h) { return __uint_as_float((unsigned)h << 16); }
; __device__ __forceinline__ float sigm(float x) { return __builtin_amdgcn_rcpf(1.f + __expf(-x)); }
; #define p (kparams())
; __device__ __forceinline__ void conv4(const bf16_t* tile, const float* cw, int ch, int tq, float (&o)[4]) {
;   const float w0 = cw[ch], w1 = cw[1536 + ch], w2 = cw[3072 + ch];
;   float xs[6];
; #pragma unroll
;   for (int i = 0; i < 6; ++i) xs[i] = bf2f(tile[(tq * 4 + i) * RPS + ch]);
; #pragma unroll
;   for (int j = 0; j < 4; ++j) o[j] = w0 * xs[j] + w1 * xs[j + 1] + w2 * xs[j + 2];
; __device__ __forceinline__ void rwkv_prep_item(const int wv_, KPR p, int l, int item, bf16_t* tile) {
;     ...
;     float r4[4], k4[4], v4[4]; conv4(tile, cw, c, tq, r4); conv4(tile, cw, 512 + c, tq, k4); conv4(tile, cw, 1024 + c, tq, v4);
;     const float kkw = p->in[I_RWKK][l * C + c];
;     const float ka = p->in[I_RWKA][l * C + c];
;     const float w00 = p->in[I_RWW0][(l * 2 + 0) * C + c], w01 = p->in[I_RWW0][(l * 2 + 1) * C + c];
;     const float a00 = p->in[I_RWA0][(l * 2 + 0) * C + c], a01 = p->in[I_RWA0][(l * 2 + 1) * C + c];
; #pragma unroll
;     for (int j = 0; j < 4; ++j) { const size_t o = (size_t)(R0 + tq * 4 + j) * 512 + c;
;       const float kn = k4[j] * kkw * inv[j];
;       PRE[0 * AE + o] = f2h(r4[j]); PRE[1 * AE + o] = f2h(v4[j]); PRE[2 * AE + o] = f2h(kn);
; #pragma unroll
;       for (int d = 0; d < 2; ++d) { const float wpre = (d == 0 ? w00 : w01) + accw[d][j];
;         const float u = 1.f - __expf(-0.6065306597f * sigm(wpre));
;         const float a = sigm((d == 0 ? a00 : a01) + acca[d][j]);
;         PRE[(3 + d) * AE + o] = f2h(u); PRE[(5 + d) * AE + o] = f2h(kn * a); PRE[(7 + d) * AE + o] = f2h(k4[j] * (1.f + (a - 1.f) * ka)); }
;       PRE[9 * AE + o] = f2h(accg[j]); } }
	v_lshlrev_b32_e32 v114, 16, v100
	ds_read_u16 v100, v106 offset:16544
	s_waitcnt lgkmcnt(0)
	v_lshlrev_b32_e32 v115, 16, v100
	s_waitcnt vmcnt(1)
	v_mul_f32_e32 v116, v91, v101
	v_fmac_f32_e32 v116, v111, v95
	v_mul_f32_e32 v100, v91, v112
	v_mul_f32_e32 v95, v91, v113
	v_mul_f32_e32 v91, v91, v114
	v_fmac_f32_e32 v100, v111, v101
	v_fmac_f32_e32 v95, v111, v112
	v_fmac_f32_e32 v91, v111, v113
	s_waitcnt vmcnt(0)
	v_fmac_f32_e32 v116, v94, v112
	v_fmac_f32_e32 v100, v94, v113
	v_fmac_f32_e32 v95, v94, v114
	v_fmac_f32_e32 v91, v94, v115
	global_load_dword v111, v[96:97], off
	s_nop 0
	global_load_dword v97, v[104:105], off offset:2048
	global_load_dword v94, v[102:103], off
	ds_read_u16 v96, v106 offset:2048
	s_waitcnt lgkmcnt(0)
	v_lshlrev_b32_e32 v102, 16, v96
	ds_read_u16 v96, v106 offset:5152
	s_waitcnt lgkmcnt(0)
	v_lshlrev_b32_e32 v103, 16, v96
	ds_read_u16 v96, v106 offset:8256
	s_waitcnt lgkmcnt(0)
	v_lshlrev_b32_e32 v112, 16, v96
	ds_read_u16 v96, v106 offset:11360
	s_waitcnt lgkmcnt(0)
	v_lshlrev_b32_e32 v113, 16, v96
	ds_read_u16 v96, v106 offset:14464
	s_waitcnt lgkmcnt(0)
	v_lshlrev_b32_e32 v101, 16, v96
	ds_read_u16 v96, v106 offset:17568
	s_waitcnt lgkmcnt(0)
	v_lshlrev_b32_e32 v96, 16, v96
	s_waitcnt vmcnt(1)
	v_mul_f32_e32 v106, v97, v103
	v_fmac_f32_e32 v106, v111, v102
	v_mul_f32_e32 v114, v97, v112
	v_add_u32_e32 v102, s78, v84
	v_fmac_f32_e32 v114, v111, v103
	v_ashrrev_i32_e32 v103, 31, v102
	v_lshlrev_b64 v[102:103], 2, v[102:103]
	v_lshl_add_u64 v[104:105], s[10:11], 0, v[102:103]
	v_lshl_add_u64 v[102:103], s[12:13], 0, v[102:103]
	global_load_dword v117, v[102:103], off
	v_add_u32_e32 v102, s22, v84
	v_ashrrev_i32_e32 v103, 31, v102
	v_mul_f32_e32 v115, v97, v113
	v_mul_f32_e32 v97, v97, v101
	v_lshlrev_b64 v[102:103], 2, v[102:103]
	v_fmac_f32_e32 v115, v111, v112
	v_fmac_f32_e32 v97, v111, v113
	global_load_dword v111, v[104:105], off
	v_lshl_add_u64 v[104:105], s[14:15], 0, v[102:103]
	global_load_dword v118, v[104:105], off
	global_load_dword v119, v[104:105], off offset:2048
	v_lshl_add_u64 v[102:103], s[18:19], 0, v[102:103]
	global_load_dword v120, v[102:103], off
	global_load_dword v121, v[102:103], off offset:2048
	v_lshl_add_u64 v[102:103], v[84:85], 1, s[16:17]
	v_lshl_add_u64 v[104:105], v[102:103], 0, v[76:77]
	s_waitcnt vmcnt(6)
	v_fma_mixlo_f16 v109, v94, v112, v106
	v_add_co_u32_e32 v106, vcc, s55, v104
	global_store_short v[104:105], v107, off
	s_nop 0
	v_addc_co_u32_e32 v107, vcc, 0, v105, vcc
	global_store_short v[106:107], v109, off
	v_add_co_u32_e32 v106, vcc, s48, v104
	v_add_u32_e32 v84, 16, v84
	s_nop 0
	v_addc_co_u32_e32 v107, vcc, 0, v105, vcc
	s_waitcnt vmcnt(6)
	v_mul_f32_e32 v85, v116, v111
	s_waitcnt vmcnt(5)
	v_add_f32_e32 v68, v68, v118
	v_mul_f32_e32 v68, 0xbfb8aa3b, v68
	v_exp_f32_e32 v68, v68
	s_waitcnt vmcnt(4)
	v_add_f32_e32 v60, v60, v119
	v_mul_f32_e32 v60, 0xbfb8aa3b, v60
	v_exp_f32_e32 v60, v60
	v_add_f32_e32 v68, 1.0, v68
	v_rcp_f32_e32 v68, v68
	s_waitcnt vmcnt(3)
	v_add_f32_e32 v64, v64, v120
	v_add_f32_e32 v60, 1.0, v60
	v_mul_f32_e32 v64, 0xbfb8aa3b, v64
	v_mul_f32_e32 v68, 0xbf1b4598, v68
	v_mul_f32_e32 v68, 0x3fb8aa3b, v68
	v_exp_f32_e32 v68, v68
	v_rcp_f32_e32 v60, v60
	v_exp_f32_e32 v64, v64
	s_waitcnt vmcnt(2)
	v_add_f32_e32 v56, v56, v121
	v_sub_f32_e32 v68, 1.0, v68
	v_mul_f32_e32 v60, 0xbf1b4598, v60
	v_add_f32_e32 v64, 1.0, v64
	v_cvt_f16_f32_e32 v68, v68
	v_mul_f32_e32 v60, 0x3fb8aa3b, v60
	v_mul_f32_e32 v122, v89, v85
	v_fma_mixlo_f16 v85, v89, v85, 0
	v_rcp_f32_e32 v64, v64
	v_exp_f32_e32 v60, v60
	v_mul_f32_e32 v56, 0xbfb8aa3b, v56
	global_store_short v[106:107], v85, off
	v_add_co_u32_e32 v106, vcc, s49, v104
	v_exp_f32_e32 v56, v56
	s_nop 0
	v_addc_co_u32_e32 v107, vcc, 0, v105, vcc
	global_store_short v[106:107], v68, off
	v_add_co_u32_e32 v106, vcc, s60, v104
	v_fma_mixlo_f16 v68, v122, v64, 0
	s_nop 0
	v_addc_co_u32_e32 v107, vcc, 0, v105, vcc
	v_add_f32_e32 v64, -1.0, v64
	v_sub_f32_e32 v60, 1.0, v60
	global_store_short v[106:107], v68, off
	v_fma_f32 v64, v117, v64, 1.0
	v_add_co_u32_e32 v106, vcc, s61, v104
	v_add_f32_e32 v56, 1.0, v56
	v_cvt_f16_f32_e32 v60, v60
	v_fma_mixlo_f16 v64, v116, v64, 0
	v_addc_co_u32_e32 v107, vcc, 0, v105, vcc
	v_rcp_f32_e32 v56, v56
	global_store_short v[106:107], v64, off
	v_add_co_u32_e32 v106, vcc, s3, v104
	s_nop 1
	v_addc_co_u32_e32 v107, vcc, 0, v105, vcc
	global_store_short v[106:107], v60, off
	v_add_co_u32_e32 v106, vcc, s74, v104
	v_fma_mixlo_f16 v60, v122, v56, 0
	s_nop 0
	v_addc_co_u32_e32 v107, vcc, 0, v105, vcc
	global_store_short v[106:107], v60, off
	v_add_co_u32_e32 v106, vcc, s65, v104
	v_add_f32_e32 v56, -1.0, v56
	s_nop 0
	v_addc_co_u32_e32 v107, vcc, 0, v105, vcc
	v_add_co_u32_e32 v104, vcc, s62, v104
	v_fma_f32 v56, v117, v56, 1.0
	s_nop 0
	v_addc_co_u32_e32 v105, vcc, 0, v105, vcc
	v_fma_mixlo_f16 v56, v116, v56, 0
	global_store_short v[104:105], v52, off
	v_lshl_add_u64 v[104:105], v[102:103], 0, v[78:79]
	global_store_short v[106:107], v56, off
	v_fma_mixlo_f16 v56, v90, v108, v110
	v_add_co_u32_e32 v106, vcc, s55, v104
	global_store_short v[104:105], v56, off
	v_fma_mixlo_f16 v56, v94, v113, v114
	v_addc_co_u32_e32 v107, vcc, 0, v105, vcc
	v_mul_f32_e32 v52, v100, v111
	global_store_short v[106:107], v56, off
	v_add_co_u32_e32 v106, vcc, s48, v104
	v_mul_f32_e32 v60, v88, v52
	v_fma_mixlo_f16 v52, v88, v52, 0
	v_addc_co_u32_e32 v107, vcc, 0, v105, vcc
	global_store_short v[106:107], v52, off
	v_add_f32_e32 v52, v69, v118
	v_mul_f32_e32 v52, 0xbfb8aa3b, v52
	v_exp_f32_e32 v52, v52
	v_add_f32_e32 v56, v65, v120
	v_mul_f32_e32 v56, 0xbfb8aa3b, v56
	v_exp_f32_e32 v56, v56
	v_add_f32_e32 v52, 1.0, v52
; __device__ __forceinline__ float sigm(float x) { return __builtin_amdgcn_rcpf(1.f + __expf(-x)); }
; __device__ __forceinline__ void rwkv_prep_item(const int wv_, KPR p, int l, int item, bf16_t* tile) {
;     ...
;     for (int j = 0; j < 4; ++j) { const size_t o = (size_t)(R0 + tq * 4 + j) * 512 + c;
;       const float kn = k4[j] * kkw * inv[j];
;       PRE[0 * AE + o] = f2h(r4[j]); PRE[1 * AE + o] = f2h(v4[j]); PRE[2 * AE + o] = f2h(kn);
; #pragma unroll
;       for (int d = 0; d < 2; ++d) { const float wpre = (d == 0 ? w00 : w01) + accw[d][j];
;         const float u = 1.f - __expf(-0.6065306597f * sigm(wpre));
;         const float a = sigm((d == 0 ? a00 : a01) + acca[d][j]);
;         PRE[(3 + d) * AE + o] = f2h(u); PRE[(5 + d) * AE + o] = f2h(kn * a); PRE[(7 + d) * AE + o] = f2h(k4[j] * (1.f + (a - 1.f) * ka)); }
;       PRE[9 * AE + o] = f2h(accg[j]); } }
;   __syncthreads();
	v_rcp_f32_e32 v52, v52
	v_add_co_u32_e32 v64, vcc, s49, v104
	v_add_f32_e32 v56, 1.0, v56
	v_mul_f32_e32 v52, 0xbf1b4598, v52
	v_mul_f32_e32 v52, 0x3fb8aa3b, v52
	v_exp_f32_e32 v52, v52
	v_rcp_f32_e32 v56, v56
	v_addc_co_u32_e32 v65, vcc, 0, v105, vcc
	v_sub_f32_e32 v52, 1.0, v52
	v_cvt_f16_f32_e32 v52, v52
	global_store_short v[64:65], v52, off
	v_add_co_u32_e32 v64, vcc, s60, v104
	v_fma_mixlo_f16 v52, v60, v56, 0
	s_nop 0
	v_addc_co_u32_e32 v65, vcc, 0, v105, vcc
	global_store_short v[64:65], v52, off
	v_add_f32_e32 v52, -1.0, v56
	v_fma_f32 v52, v117, v52, 1.0
	v_add_co_u32_e32 v64, vcc, s61, v104
	v_fma_mixlo_f16 v52, v100, v52, 0
	s_nop 0
	v_addc_co_u32_e32 v65, vcc, 0, v105, vcc
	global_store_short v[64:65], v52, off
	v_add_f32_e32 v52, v61, v119
	v_mul_f32_e32 v52, 0xbfb8aa3b, v52
	v_exp_f32_e32 v52, v52
	v_add_f32_e32 v56, v57, v121
	v_mul_f32_e32 v56, 0xbfb8aa3b, v56
	v_exp_f32_e32 v56, v56
	v_add_f32_e32 v52, 1.0, v52
	v_rcp_f32_e32 v52, v52
	v_fma_mixlo_f16 v64, v94, v101, v115
	v_add_f32_e32 v56, 1.0, v56
	v_rcp_f32_e32 v61, v56
	v_mul_f32_e32 v52, 0xbf1b4598, v52
	v_mul_f32_e32 v52, 0x3fb8aa3b, v52
	v_exp_f32_e32 v52, v52
	v_add_co_u32_e32 v56, vcc, s3, v104
	v_sub_f32_e32 v52, 1.0, v52
	v_cvt_f16_f32_e32 v52, v52
	v_addc_co_u32_e32 v57, vcc, 0, v105, vcc
	global_store_short v[56:57], v52, off
	v_add_co_u32_e32 v56, vcc, s74, v104
	v_fma_mixlo_f16 v52, v60, v61, 0
	s_nop 0
	v_addc_co_u32_e32 v57, vcc, 0, v105, vcc
	global_store_short v[56:57], v52, off
	v_add_f32_e32 v52, -1.0, v61
	v_fma_f32 v52, v117, v52, 1.0
	v_add_co_u32_e32 v56, vcc, s65, v104
	v_fma_mixlo_f16 v52, v100, v52, 0
	s_nop 0
	v_addc_co_u32_e32 v57, vcc, 0, v105, vcc
	global_store_short v[56:57], v52, off
	v_cvt_f16_f32_e32 v56, v53
	v_add_co_u32_e32 v52, vcc, s62, v104
	v_mul_f32_e32 v60, v95, v111
	s_nop 0
	v_addc_co_u32_e32 v53, vcc, 0, v105, vcc
	global_store_short v[52:53], v56, off
	v_fma_mixlo_f16 v56, v90, v98, v99
	v_lshl_add_u64 v[52:53], v[102:103], 0, v[80:81]
	global_store_short v[52:53], v56, off
	v_add_co_u32_e32 v56, vcc, s55, v52
	v_mul_f32_e32 v61, v87, v60
	s_nop 0
	v_addc_co_u32_e32 v57, vcc, 0, v53, vcc
	global_store_short v[56:57], v64, off
	v_add_co_u32_e32 v56, vcc, s48, v52
	v_fma_mixlo_f16 v60, v87, v60, 0
	s_nop 0
	v_addc_co_u32_e32 v57, vcc, 0, v53, vcc
	global_store_short v[56:57], v60, off
	v_add_f32_e32 v56, v70, v118
	v_mul_f32_e32 v56, 0xbfb8aa3b, v56
	v_exp_f32_e32 v56, v56
	v_add_f32_e32 v57, v66, v120
	v_mul_f32_e32 v57, 0xbfb8aa3b, v57
	v_exp_f32_e32 v57, v57
	v_add_f32_e32 v56, 1.0, v56
	v_rcp_f32_e32 v56, v56
	v_add_f32_e32 v57, 1.0, v57
	v_rcp_f32_e32 v60, v57
	v_mul_f32_e32 v56, 0xbf1b4598, v56
	v_mul_f32_e32 v56, 0x3fb8aa3b, v56
	v_exp_f32_e32 v56, v56
	s_nop 0
	v_sub_f32_e32 v56, 1.0, v56
	v_cvt_f16_f32_e32 v64, v56
	v_add_co_u32_e32 v56, vcc, s49, v52
	s_nop 1
	v_addc_co_u32_e32 v57, vcc, 0, v53, vcc
	global_store_short v[56:57], v64, off
	v_add_co_u32_e32 v56, vcc, s60, v52
	v_fma_mixlo_f16 v64, v61, v60, 0
	s_nop 0
	v_addc_co_u32_e32 v57, vcc, 0, v53, vcc
	global_store_short v[56:57], v64, off
	v_add_f32_e32 v56, -1.0, v60
	v_fma_f32 v56, v117, v56, 1.0
	v_fma_mixlo_f16 v60, v95, v56, 0
	v_add_co_u32_e32 v56, vcc, s61, v52
	s_nop 1
	v_addc_co_u32_e32 v57, vcc, 0, v53, vcc
	global_store_short v[56:57], v60, off
	v_add_f32_e32 v56, v62, v119
	v_mul_f32_e32 v56, 0xbfb8aa3b, v56
	v_exp_f32_e32 v56, v56
	v_add_f32_e32 v57, v58, v121
	v_mul_f32_e32 v57, 0xbfb8aa3b, v57
	v_exp_f32_e32 v57, v57
	v_add_f32_e32 v56, 1.0, v56
	v_rcp_f32_e32 v56, v56
	v_add_f32_e32 v57, 1.0, v57
	v_rcp_f32_e32 v58, v57
	v_mul_f32_e32 v56, 0xbf1b4598, v56
	v_mul_f32_e32 v56, 0x3fb8aa3b, v56
	v_exp_f32_e32 v56, v56
	s_nop 0
	v_sub_f32_e32 v56, 1.0, v56
	v_cvt_f16_f32_e32 v60, v56
	v_add_co_u32_e32 v56, vcc, s3, v52
	s_nop 1
	v_addc_co_u32_e32 v57, vcc, 0, v53, vcc
	global_store_short v[56:57], v60, off
	v_add_co_u32_e32 v56, vcc, s74, v52
	v_fma_mixlo_f16 v60, v61, v58, 0
	s_nop 0
	v_addc_co_u32_e32 v57, vcc, 0, v53, vcc
	global_store_short v[56:57], v60, off
	v_add_f32_e32 v56, -1.0, v58
	v_fma_f32 v56, v117, v56, 1.0
	v_fma_mixlo_f16 v58, v95, v56, 0
	v_add_co_u32_e32 v56, vcc, s65, v52
	v_fma_mixlo_f16 v60, v94, v96, v97
	s_nop 0
	v_addc_co_u32_e32 v57, vcc, 0, v53, vcc
	v_add_co_u32_e32 v52, vcc, s62, v52
	global_store_short v[56:57], v58, off
	s_nop 0
	v_addc_co_u32_e32 v53, vcc, 0, v53, vcc
	global_store_short v[52:53], v54, off
	v_fma_mixlo_f16 v56, v90, v92, v93
	v_lshl_add_u64 v[52:53], v[102:103], 0, v[82:83]
	global_store_short v[52:53], v56, off
	v_add_co_u32_e32 v56, vcc, s55, v52
	v_mul_f32_e32 v54, v91, v111
	s_nop 0
	v_addc_co_u32_e32 v57, vcc, 0, v53, vcc
	global_store_short v[56:57], v60, off
	v_add_co_u32_e32 v56, vcc, s48, v52
	v_mul_f32_e32 v58, v86, v54
	v_fma_mixlo_f16 v54, v86, v54, 0
	v_addc_co_u32_e32 v57, vcc, 0, v53, vcc
	global_store_short v[56:57], v54, off
	v_add_f32_e32 v54, v71, v118
	v_mul_f32_e32 v54, 0xbfb8aa3b, v54
	v_exp_f32_e32 v54, v54
	v_add_f32_e32 v56, v67, v120
	v_mul_f32_e32 v56, 0xbfb8aa3b, v56
	v_exp_f32_e32 v56, v56
	v_add_f32_e32 v54, 1.0, v54
	v_rcp_f32_e32 v54, v54
	v_add_f32_e32 v56, 1.0, v56
	v_rcp_f32_e32 v60, v56
	v_mul_f32_e32 v54, 0xbf1b4598, v54
	v_mul_f32_e32 v54, 0x3fb8aa3b, v54
	v_exp_f32_e32 v54, v54
	v_add_co_u32_e32 v56, vcc, s49, v52
	v_sub_f32_e32 v54, 1.0, v54
	v_cvt_f16_f32_e32 v54, v54
	v_addc_co_u32_e32 v57, vcc, 0, v53, vcc
	global_store_short v[56:57], v54, off
	v_add_co_u32_e32 v56, vcc, s60, v52
	v_fma_mixlo_f16 v54, v58, v60, 0
	s_nop 0
	v_addc_co_u32_e32 v57, vcc, 0, v53, vcc
	global_store_short v[56:57], v54, off
	v_add_f32_e32 v54, -1.0, v60
	v_fma_f32 v54, v117, v54, 1.0
	v_add_co_u32_e32 v56, vcc, s61, v52
	v_fma_mixlo_f16 v54, v91, v54, 0
	s_nop 0
	v_addc_co_u32_e32 v57, vcc, 0, v53, vcc
	global_store_short v[56:57], v54, off
	v_add_f32_e32 v54, v63, v119
	v_mul_f32_e32 v54, 0xbfb8aa3b, v54
	v_exp_f32_e32 v54, v54
	v_add_f32_e32 v56, v59, v121
	v_mul_f32_e32 v56, 0xbfb8aa3b, v56
	v_exp_f32_e32 v56, v56
	v_add_f32_e32 v54, 1.0, v54
	v_rcp_f32_e32 v54, v54
	v_add_f32_e32 v56, 1.0, v56
	v_rcp_f32_e32 v59, v56
	v_mul_f32_e32 v54, 0xbf1b4598, v54
	v_mul_f32_e32 v54, 0x3fb8aa3b, v54
	v_exp_f32_e32 v54, v54
	v_add_co_u32_e32 v56, vcc, s3, v52
	v_sub_f32_e32 v54, 1.0, v54
	v_cvt_f16_f32_e32 v54, v54
	v_addc_co_u32_e32 v57, vcc, 0, v53, vcc
	global_store_short v[56:57], v54, off
	v_add_co_u32_e32 v56, vcc, s74, v52
	v_fma_mixlo_f16 v54, v58, v59, 0
	s_nop 0
	v_addc_co_u32_e32 v57, vcc, 0, v53, vcc
	global_store_short v[56:57], v54, off
	v_add_f32_e32 v54, -1.0, v59
	v_fma_f32 v54, v117, v54, 1.0
	v_add_co_u32_e32 v56, vcc, 0x8800000, v52
	v_fma_mixlo_f16 v54, v91, v54, 0
	s_nop 0
	v_addc_co_u32_e32 v57, vcc, 0, v53, vcc
	global_store_short v[56:57], v54, off
	v_cvt_f16_f32_e32 v54, v55
	v_add_co_u32_e32 v52, vcc, 0x9900000, v52
	s_nop 1
	v_addc_co_u32_e32 v53, vcc, 0, v53, vcc
	global_store_short v[52:53], v54, off
	s_cbranch_scc1 .LBB0_457
	s_add_i32 s23, s23, 1
	s_cmp_lg_u32 s23, 3
	s_barrier
	s_cbranch_scc1 .LBB0_441

; #define p (kparams())
; __device__ __forceinline__ void rwkv_prep_item(const int wv_, KPR p, int l, int item, bf16_t* tile) {
;     ...
;   for (int nt = 0; nt < 4; ++nt) { const int c = wid * 64 + nt * 16 + cl;
;     f32x4 accw[2], acca[2], accg = (f32x4){0.f, 0.f, 0.f, 0.f};
; #pragma unroll
;     for (int d = 0; d < 2; ++d) { accw[d] = (f32x4){0.f, 0.f, 0.f, 0.f}; acca[d] = (f32x4){0.f, 0.f, 0.f, 0.f};
; #pragma unroll
;       for (int ks = 0; ks < 2; ++ks) {
;         accw[d] = __builtin_amdgcn_mfma_f32_16x16x32_bf16(aw[d][ks], ld_frag(W2T + ((size_t)d * C + c) * 64 + ks * 32 + tq * 8), accw[d], 0, 0, 0);
;         acca[d] = __builtin_amdgcn_mfma_f32_16x16x32_bf16(aa[d][ks], ld_frag(A2T + ((size_t)d * C + c) * 64 + ks * 32 + tq * 8), acca[d], 0, 0, 0); } }
; #pragma unroll
;     for (int ks = 0; ks < 4; ++ks) accg = __builtin_amdgcn_mfma_f32_16x16x32_bf16(ag[ks], ld_frag(G2T + (size_t)c * 128 + ks * 32 + tq * 8), accg, 0, 0, 0);
;     float r4[4], k4[4], v4[4]; conv4(tile, cw, c, tq, r4); conv4(tile, cw, 512 + c, tq, k4); conv4(tile, cw, 1024 + c, tq, v4);
;     const float kkw = p->in[I_RWKK][l * C + c];
;     const float ka = p->in[I_RWKA][l * C + c];
;     const float w00 = p->in[I_RWW0][(l * 2 + 0) * C + c], w01 = p->in[I_RWW0][(l * 2 + 1) * C + c];
;     const float a00 = p->in[I_RWA0][(l * 2 + 0) * C + c], a01 = p->in[I_RWA0][(l * 2 + 1) * C + c];
.LBB0_477:
	v_ashrrev_i32_e32 v85, 31, v84
	v_lshl_add_u64 v[126:127], v[84:85], 2, s[4:5]
	global_load_dword v132, v[126:127], off
	global_load_dword v133, v[126:127], off offset:2048
	v_add_co_u32_e32 v128, vcc, s52, v126
	s_nop 1
	v_addc_co_u32_e32 v129, vcc, 0, v127, vcc
	global_load_dword v134, v[128:129], off offset:2048
	global_load_dword v135, v[128:129], off
	v_add_co_u32_e32 v128, vcc, s80, v126
	s_nop 1
	v_addc_co_u32_e32 v129, vcc, 0, v127, vcc
	global_load_dword v136, v[128:129], off offset:-4096
	global_load_dword v137, v[128:129], off
	v_add_co_u32_e32 v128, vcc, s63, v126
	s_nop 1
	v_addc_co_u32_e32 v129, vcc, 0, v127, vcc
	global_load_dword v138, v[128:129], off
	global_load_dword v139, v[128:129], off offset:2048
	v_add_co_u32_e32 v128, vcc, s54, v126
	s_nop 1
	v_addc_co_u32_e32 v129, vcc, 0, v127, vcc
	global_load_dword v140, v[128:129], off offset:2048
	s_waitcnt lgkmcnt(0)
	v_add_u32_e32 v130, s78, v84
	v_ashrrev_i32_e32 v131, 31, v130
	v_lshlrev_b64 v[130:131], 2, v[130:131]
	v_lshl_add_u64 v[128:129], s[12:13], 0, v[130:131]
	global_load_dword v141, v[128:129], off
	v_lshl_add_u64 v[128:129], s[10:11], 0, v[130:131]
	global_load_dword v142, v[128:129], off
	v_add_u32_e32 v130, s9, v84
	v_ashrrev_i32_e32 v131, 31, v130
	v_lshlrev_b64 v[130:131], 2, v[130:131]
	v_lshl_add_u64 v[128:129], s[14:15], 0, v[130:131]
	global_load_dword v143, v[128:129], off
	global_load_dword v144, v[128:129], off offset:2048
	v_lshl_add_u64 v[128:129], s[18:19], 0, v[130:131]
	global_load_dword v145, v[128:129], off
	global_load_dword v146, v[128:129], off offset:2048
	v_lshlrev_b64 v[52:53], 7, v[84:85]
	v_lshl_add_u64 v[90:91], v[0:1], 0, v[52:53]
	v_lshl_add_u64 v[92:93], v[72:73], 0, v[52:53]
	v_lshl_add_u64 v[238:239], v[90:91], 0, s[92:93]
	v_lshl_add_u64 v[240:241], v[92:93], 0, s[92:93]
	v_lshlrev_b64 v[52:53], 8, v[84:85]
	v_lshl_add_u64 v[124:125], v[74:75], 0, v[52:53]
	global_load_dwordx4 v[190:193], v[90:91], off
	global_load_dwordx4 v[194:197], v[90:91], off offset:64
	global_load_dwordx4 v[198:201], v[92:93], off
	global_load_dwordx4 v[202:205], v[92:93], off offset:64
	global_load_dwordx4 v[206:209], v[238:239], off
	global_load_dwordx4 v[210:213], v[238:239], off offset:64
	global_load_dwordx4 v[214:217], v[240:241], off
	global_load_dwordx4 v[218:221], v[240:241], off offset:64
	global_load_dwordx4 v[222:225], v[124:125], off
	global_load_dwordx4 v[226:229], v[124:125], off offset:64
	global_load_dwordx4 v[230:233], v[124:125], off offset:128
	global_load_dwordx4 v[234:237], v[124:125], off offset:192
	v_add_u32_e32 v106, s20, v3
	s_add_i32 s20, s20, 32
	s_cmpk_lg_i32 s20, 0x80
	s_waitcnt vmcnt(11)
	v_mfma_f32_16x16x32_bf16 v[68:71], v[4:7], v[190:193], 0
	s_waitcnt vmcnt(10)
	v_mfma_f32_16x16x32_bf16 v[68:71], v[12:15], v[194:197], v[68:71]
	s_waitcnt vmcnt(9)
	v_mfma_f32_16x16x32_bf16 v[64:67], v[8:11], v[198:201], 0
	s_waitcnt vmcnt(8)
	v_mfma_f32_16x16x32_bf16 v[64:67], v[16:19], v[202:205], v[64:67]
	s_waitcnt vmcnt(7)
	v_mfma_f32_16x16x32_bf16 v[60:63], v[20:23], v[206:209], 0
	s_waitcnt vmcnt(6)
	v_mfma_f32_16x16x32_bf16 v[60:63], v[28:31], v[210:213], v[60:63]
	s_waitcnt vmcnt(5)
	v_mfma_f32_16x16x32_bf16 v[56:59], v[24:27], v[214:217], 0
	s_waitcnt vmcnt(4)
	v_mfma_f32_16x16x32_bf16 v[56:59], v[32:35], v[218:221], v[56:59]
	s_waitcnt vmcnt(3)
	v_mfma_f32_16x16x32_bf16 v[52:55], v[36:39], v[222:225], 0
	s_waitcnt vmcnt(2)
	v_mfma_f32_16x16x32_bf16 v[52:55], v[40:43], v[226:229], v[52:55]
	s_waitcnt vmcnt(1)
	v_mfma_f32_16x16x32_bf16 v[52:55], v[44:47], v[230:233], v[52:55]
	v_lshl_add_u64 v[94:95], v[84:85], 2, s[4:5]
	v_add_co_u32_e32 v96, vcc, s52, v94
	s_waitcnt vmcnt(0)
	v_mfma_f32_16x16x32_bf16 v[52:55], v[48:51], v[234:237], v[52:55]
	v_addc_co_u32_e32 v97, vcc, 0, v95, vcc
	global_load_dword v93, v[96:97], off offset:2048
	global_load_dword v91, v[94:95], off
	ds_read_u16 v92, v106
	v_add_co_u32_e32 v100, vcc, s54, v94
	s_nop 2
	v_cvt_f16_f32_e32 v52, v52
	v_addc_co_u32_e32 v101, vcc, 0, v95, vcc
	s_waitcnt lgkmcnt(0)
	v_lshlrev_b32_e32 v99, 16, v92
	ds_read_u16 v92, v106 offset:3104
	v_add_co_u32_e32 v102, vcc, s80, v94
	v_cvt_f16_f32_e32 v54, v54
	s_nop 0
	v_addc_co_u32_e32 v103, vcc, 0, v95, vcc
	s_waitcnt lgkmcnt(0)
	v_lshlrev_b32_e32 v104, 16, v92
	ds_read_u16 v92, v106 offset:6208
	global_load_dword v90, v[102:103], off offset:-4096
	global_load_dword v111, v[94:95], off offset:2048
	s_waitcnt lgkmcnt(0)
	v_lshlrev_b32_e32 v107, 16, v92
	ds_read_u16 v92, v106 offset:9312
	s_waitcnt lgkmcnt(0)
	v_lshlrev_b32_e32 v108, 16, v92
	ds_read_u16 v92, v106 offset:12416
	s_waitcnt lgkmcnt(0)
	v_lshlrev_b32_e32 v98, 16, v92
	ds_read_u16 v92, v106 offset:15520
	s_waitcnt lgkmcnt(0)
	v_lshlrev_b32_e32 v92, 16, v92
	s_waitcnt vmcnt(3)
	v_mul_f32_e32 v110, v93, v107
	v_mul_f32_e32 v109, v93, v104
	s_waitcnt vmcnt(2)
	v_fmac_f32_e32 v110, v91, v104
	v_add_co_u32_e32 v104, vcc, s63, v94
	v_fmac_f32_e32 v109, v91, v99
	v_mul_f32_e32 v99, v93, v108
	v_mul_f32_e32 v93, v93, v98
	v_addc_co_u32_e32 v105, vcc, 0, v95, vcc
	v_fmac_f32_e32 v99, v91, v107
	v_fmac_f32_e32 v93, v91, v108
	global_load_dword v91, v[104:105], off
	global_load_dword v94, v[100:101], off offset:2048
	ds_read_u16 v95, v106 offset:1024
	ds_read_u16 v100, v106 offset:4128
	s_waitcnt vmcnt(3)
	v_fma_mixlo_f16 v107, v90, v107, v109
	s_waitcnt lgkmcnt(1)
	v_lshlrev_b32_e32 v95, 16, v95
	s_waitcnt lgkmcnt(0)
	v_lshlrev_b32_e32 v101, 16, v100
	ds_read_u16 v100, v106 offset:7232
	s_waitcnt lgkmcnt(0)
	v_lshlrev_b32_e32 v112, 16, v100
	ds_read_u16 v100, v106 offset:10336
	s_waitcnt lgkmcnt(0)
	v_lshlrev_b32_e32 v113, 16, v100
	ds_read_u16 v100, v106 offset:13440
	s_waitcnt lgkmcnt(0)
; __device__ __forceinline__ float bf2f(bf16_t h) { return __uint_as_float((unsigned)h << 16); }
; __device__ __forceinline__ float sigm(float x) { return __builtin_amdgcn_rcpf(1.f + __expf(-x)); }
; #define p (kparams())
; __device__ __forceinline__ void conv4(const bf16_t* tile, const float* cw, int ch, int tq, float (&o)[4]) {
;   const float w0 = cw[ch], w1 = cw[1536 + ch], w2 = cw[3072 + ch];
;   float xs[6];
; #pragma unroll
;   for (int i = 0; i < 6; ++i) xs[i] = bf2f(tile[(tq * 4 + i) * RPS + ch]);
; #pragma unroll
;   for (int j = 0; j < 4; ++j) o[j] = w0 * xs[j] + w1 * xs[j + 1] + w2 * xs[j + 2];
; __device__ __forceinline__ void rwkv_prep_item(const int wv_, KPR p, int l, int item, bf16_t* tile) {
;     ...
;     float r4[4], k4[4], v4[4]; conv4(tile, cw, c, tq, r4); conv4(tile, cw, 512 + c, tq, k4); conv4(tile, cw, 1024 + c, tq, v4);
;     const float kkw = p->in[I_RWKK][l * C + c];
;     const float ka = p->in[I_RWKA][l * C + c];
;     const float w00 = p->in[I_RWW0][(l * 2 + 0) * C + c], w01 = p->in[I_RWW0][(l * 2 + 1) * C + c];
;     const float a00 = p->in[I_RWA0][(l * 2 + 0) * C + c], a01 = p->in[I_RWA0][(l * 2 + 1) * C + c];
; #pragma unroll
;     for (int j = 0; j < 4; ++j) { const size_t o = (size_t)(R0 + tq * 4 + j) * 512 + c;
;       const float kn = k4[j] * kkw * inv[j];
;       PRE[0 * AE + o] = f2h(r4[j]); PRE[1 * AE + o] = f2h(v4[j]); PRE[2 * AE + o] = f2h(kn);
; #pragma unroll
;       for (int d = 0; d < 2; ++d) { const float wpre = (d == 0 ? w00 : w01) + accw[d][j];
;         const float u = 1.f - __expf(-0.6065306597f * sigm(wpre));
;         const float a = sigm((d == 0 ? a00 : a01) + acca[d][j]);
;         PRE[(3 + d) * AE + o] = f2h(u); PRE[(5 + d) * AE + o] = f2h(kn * a); PRE[(7 + d) * AE + o] = f2h(k4[j] * (1.f + (a - 1.f) * ka)); }
;       PRE[9 * AE + o] = f2h(accg[j]); } }
	v_lshlrev_b32_e32 v114, 16, v100
	ds_read_u16 v100, v106 offset:16544
	s_waitcnt lgkmcnt(0)
	v_lshlrev_b32_e32 v115, 16, v100
	s_waitcnt vmcnt(1)
	v_mul_f32_e32 v116, v91, v101
	v_fmac_f32_e32 v116, v111, v95
	v_mul_f32_e32 v100, v91, v112
	v_mul_f32_e32 v95, v91, v113
	v_mul_f32_e32 v91, v91, v114
	v_fmac_f32_e32 v100, v111, v101
	v_fmac_f32_e32 v95, v111, v112
	v_fmac_f32_e32 v91, v111, v113
	s_waitcnt vmcnt(0)
	v_fmac_f32_e32 v116, v94, v112
	v_fmac_f32_e32 v100, v94, v113
	v_fmac_f32_e32 v95, v94, v114
	v_fmac_f32_e32 v91, v94, v115
	global_load_dword v111, v[96:97], off
	s_nop 0
	global_load_dword v97, v[104:105], off offset:2048
	global_load_dword v94, v[102:103], off
	ds_read_u16 v96, v106 offset:2048
	s_waitcnt lgkmcnt(0)
	v_lshlrev_b32_e32 v102, 16, v96
	ds_read_u16 v96, v106 offset:5152
	s_waitcnt lgkmcnt(0)
	v_lshlrev_b32_e32 v103, 16, v96
	ds_read_u16 v96, v106 offset:8256
	s_waitcnt lgkmcnt(0)
	v_lshlrev_b32_e32 v112, 16, v96
	ds_read_u16 v96, v106 offset:11360
	s_waitcnt lgkmcnt(0)
	v_lshlrev_b32_e32 v113, 16, v96
	ds_read_u16 v96, v106 offset:14464
	s_waitcnt lgkmcnt(0)
	v_lshlrev_b32_e32 v101, 16, v96
	ds_read_u16 v96, v106 offset:17568
	s_waitcnt lgkmcnt(0)
	v_lshlrev_b32_e32 v96, 16, v96
	s_waitcnt vmcnt(1)
	v_mul_f32_e32 v106, v97, v103
	v_fmac_f32_e32 v106, v111, v102
	v_mul_f32_e32 v114, v97, v112
	v_add_u32_e32 v102, s78, v84
	v_fmac_f32_e32 v114, v111, v103
	v_ashrrev_i32_e32 v103, 31, v102
	v_lshlrev_b64 v[102:103], 2, v[102:103]
	v_lshl_add_u64 v[104:105], s[10:11], 0, v[102:103]
	v_lshl_add_u64 v[102:103], s[12:13], 0, v[102:103]
	global_load_dword v117, v[102:103], off
	v_add_u32_e32 v102, s9, v84
	v_ashrrev_i32_e32 v103, 31, v102
	v_mul_f32_e32 v115, v97, v113
	v_mul_f32_e32 v97, v97, v101
	v_lshlrev_b64 v[102:103], 2, v[102:103]
	v_fmac_f32_e32 v115, v111, v112
	v_fmac_f32_e32 v97, v111, v113
	global_load_dword v111, v[104:105], off
	v_lshl_add_u64 v[104:105], s[14:15], 0, v[102:103]
	global_load_dword v118, v[104:105], off
	global_load_dword v119, v[104:105], off offset:2048
	v_lshl_add_u64 v[102:103], s[18:19], 0, v[102:103]
	global_load_dword v120, v[102:103], off
	global_load_dword v121, v[102:103], off offset:2048
	v_lshl_add_u64 v[102:103], v[84:85], 1, s[16:17]
	v_lshl_add_u64 v[104:105], v[102:103], 0, v[76:77]
	s_waitcnt vmcnt(6)
	v_fma_mixlo_f16 v109, v94, v112, v106
	v_add_co_u32_e32 v106, vcc, s55, v104
	global_store_short v[104:105], v107, off
	s_nop 0
	v_addc_co_u32_e32 v107, vcc, 0, v105, vcc
	global_store_short v[106:107], v109, off
	v_add_co_u32_e32 v106, vcc, s48, v104
	v_add_u32_e32 v84, 16, v84
	s_nop 0
	v_addc_co_u32_e32 v107, vcc, 0, v105, vcc
	s_waitcnt vmcnt(6)
	v_mul_f32_e32 v85, v116, v111
	s_waitcnt vmcnt(5)
	v_add_f32_e32 v68, v68, v118
	v_mul_f32_e32 v68, 0xbfb8aa3b, v68
	v_exp_f32_e32 v68, v68
	s_waitcnt vmcnt(4)
	v_add_f32_e32 v60, v60, v119
	v_mul_f32_e32 v60, 0xbfb8aa3b, v60
	v_exp_f32_e32 v60, v60
	v_add_f32_e32 v68, 1.0, v68
	v_rcp_f32_e32 v68, v68
	s_waitcnt vmcnt(3)
	v_add_f32_e32 v64, v64, v120
	v_add_f32_e32 v60, 1.0, v60
	v_mul_f32_e32 v64, 0xbfb8aa3b, v64
	v_mul_f32_e32 v68, 0xbf1b4598, v68
	v_mul_f32_e32 v68, 0x3fb8aa3b, v68
	v_exp_f32_e32 v68, v68
	v_rcp_f32_e32 v60, v60
	v_exp_f32_e32 v64, v64
	s_waitcnt vmcnt(2)
	v_add_f32_e32 v56, v56, v121
	v_sub_f32_e32 v68, 1.0, v68
	v_mul_f32_e32 v60, 0xbf1b4598, v60
	v_add_f32_e32 v64, 1.0, v64
	v_cvt_f16_f32_e32 v68, v68
	v_mul_f32_e32 v60, 0x3fb8aa3b, v60
	v_mul_f32_e32 v122, v89, v85
	v_fma_mixlo_f16 v85, v89, v85, 0
	v_rcp_f32_e32 v64, v64
	v_exp_f32_e32 v60, v60
	v_mul_f32_e32 v56, 0xbfb8aa3b, v56
	global_store_short v[106:107], v85, off
	v_add_co_u32_e32 v106, vcc, s49, v104
	v_exp_f32_e32 v56, v56
	s_nop 0
	v_addc_co_u32_e32 v107, vcc, 0, v105, vcc
	global_store_short v[106:107], v68, off
	v_add_co_u32_e32 v106, vcc, s60, v104
	v_fma_mixlo_f16 v68, v122, v64, 0
	s_nop 0
	v_addc_co_u32_e32 v107, vcc, 0, v105, vcc
	v_add_f32_e32 v64, -1.0, v64
	v_sub_f32_e32 v60, 1.0, v60
	global_store_short v[106:107], v68, off
	v_fma_f32 v64, v117, v64, 1.0
	v_add_co_u32_e32 v106, vcc, s61, v104
	v_add_f32_e32 v56, 1.0, v56
	v_cvt_f16_f32_e32 v60, v60
	v_fma_mixlo_f16 v64, v116, v64, 0
	v_addc_co_u32_e32 v107, vcc, 0, v105, vcc
	v_rcp_f32_e32 v56, v56
	global_store_short v[106:107], v64, off
	v_add_co_u32_e32 v106, vcc, s3, v104
	s_nop 1
	v_addc_co_u32_e32 v107, vcc, 0, v105, vcc
	global_store_short v[106:107], v60, off
	v_add_co_u32_e32 v106, vcc, s74, v104
	v_fma_mixlo_f16 v60, v122, v56, 0
	s_nop 0
	v_addc_co_u32_e32 v107, vcc, 0, v105, vcc
	global_store_short v[106:107], v60, off
	v_add_co_u32_e32 v106, vcc, s65, v104
	v_add_f32_e32 v56, -1.0, v56
	s_nop 0
	v_addc_co_u32_e32 v107, vcc, 0, v105, vcc
	v_add_co_u32_e32 v104, vcc, s62, v104
	v_fma_f32 v56, v117, v56, 1.0
	s_nop 0
	v_addc_co_u32_e32 v105, vcc, 0, v105, vcc
	v_fma_mixlo_f16 v56, v116, v56, 0
	global_store_short v[104:105], v52, off
	v_lshl_add_u64 v[104:105], v[102:103], 0, v[78:79]
	global_store_short v[106:107], v56, off
	v_fma_mixlo_f16 v56, v90, v108, v110
	v_add_co_u32_e32 v106, vcc, s55, v104
	global_store_short v[104:105], v56, off
	v_fma_mixlo_f16 v56, v94, v113, v114
	v_addc_co_u32_e32 v107, vcc, 0, v105, vcc
	v_mul_f32_e32 v52, v100, v111
	global_store_short v[106:107], v56, off
	v_add_co_u32_e32 v106, vcc, s48, v104
	v_mul_f32_e32 v60, v88, v52
	v_fma_mixlo_f16 v52, v88, v52, 0
	v_addc_co_u32_e32 v107, vcc, 0, v105, vcc
	global_store_short v[106:107], v52, off
	v_add_f32_e32 v52, v69, v118
	v_mul_f32_e32 v52, 0xbfb8aa3b, v52
	v_exp_f32_e32 v52, v52
	v_add_f32_e32 v56, v65, v120
	v_mul_f32_e32 v56, 0xbfb8aa3b, v56
	v_exp_f32_e32 v56, v56
	v_add_f32_e32 v52, 1.0, v52
; __device__ __forceinline__ float sigm(float x) { return __builtin_amdgcn_rcpf(1.f + __expf(-x)); }
; __device__ __forceinline__ void rwkv_prep_item(const int wv_, KPR p, int l, int item, bf16_t* tile) {
;     ...
;     for (int j = 0; j < 4; ++j) { const size_t o = (size_t)(R0 + tq * 4 + j) * 512 + c;
;       const float kn = k4[j] * kkw * inv[j];
;       PRE[0 * AE + o] = f2h(r4[j]); PRE[1 * AE + o] = f2h(v4[j]); PRE[2 * AE + o] = f2h(kn);
; #pragma unroll
;       for (int d = 0; d < 2; ++d) { const float wpre = (d == 0 ? w00 : w01) + accw[d][j];
;         const float u = 1.f - __expf(-0.6065306597f * sigm(wpre));
;         const float a = sigm((d == 0 ? a00 : a01) + acca[d][j]);
;         PRE[(3 + d) * AE + o] = f2h(u); PRE[(5 + d) * AE + o] = f2h(kn * a); PRE[(7 + d) * AE + o] = f2h(k4[j] * (1.f + (a - 1.f) * ka)); }
;       PRE[9 * AE + o] = f2h(accg[j]); } }
;   __syncthreads();
	v_rcp_f32_e32 v52, v52
	v_add_co_u32_e32 v64, vcc, s49, v104
	v_add_f32_e32 v56, 1.0, v56
	v_mul_f32_e32 v52, 0xbf1b4598, v52
	v_mul_f32_e32 v52, 0x3fb8aa3b, v52
	v_exp_f32_e32 v52, v52
	v_rcp_f32_e32 v56, v56
	v_addc_co_u32_e32 v65, vcc, 0, v105, vcc
	v_sub_f32_e32 v52, 1.0, v52
	v_cvt_f16_f32_e32 v52, v52
	global_store_short v[64:65], v52, off
	v_add_co_u32_e32 v64, vcc, s60, v104
	v_fma_mixlo_f16 v52, v60, v56, 0
	s_nop 0
	v_addc_co_u32_e32 v65, vcc, 0, v105, vcc
	global_store_short v[64:65], v52, off
	v_add_f32_e32 v52, -1.0, v56
	v_fma_f32 v52, v117, v52, 1.0
	v_add_co_u32_e32 v64, vcc, s61, v104
	v_fma_mixlo_f16 v52, v100, v52, 0
	s_nop 0
	v_addc_co_u32_e32 v65, vcc, 0, v105, vcc
	global_store_short v[64:65], v52, off
	v_add_f32_e32 v52, v61, v119
	v_mul_f32_e32 v52, 0xbfb8aa3b, v52
	v_exp_f32_e32 v52, v52
	v_add_f32_e32 v56, v57, v121
	v_mul_f32_e32 v56, 0xbfb8aa3b, v56
	v_exp_f32_e32 v56, v56
	v_add_f32_e32 v52, 1.0, v52
	v_rcp_f32_e32 v52, v52
	v_fma_mixlo_f16 v64, v94, v101, v115
	v_add_f32_e32 v56, 1.0, v56
	v_rcp_f32_e32 v61, v56
	v_mul_f32_e32 v52, 0xbf1b4598, v52
	v_mul_f32_e32 v52, 0x3fb8aa3b, v52
	v_exp_f32_e32 v52, v52
	v_add_co_u32_e32 v56, vcc, s3, v104
	v_sub_f32_e32 v52, 1.0, v52
	v_cvt_f16_f32_e32 v52, v52
	v_addc_co_u32_e32 v57, vcc, 0, v105, vcc
	global_store_short v[56:57], v52, off
	v_add_co_u32_e32 v56, vcc, s74, v104
	v_fma_mixlo_f16 v52, v60, v61, 0
	s_nop 0
	v_addc_co_u32_e32 v57, vcc, 0, v105, vcc
	global_store_short v[56:57], v52, off
	v_add_f32_e32 v52, -1.0, v61
	v_fma_f32 v52, v117, v52, 1.0
	v_add_co_u32_e32 v56, vcc, s65, v104
	v_fma_mixlo_f16 v52, v100, v52, 0
	s_nop 0
	v_addc_co_u32_e32 v57, vcc, 0, v105, vcc
	global_store_short v[56:57], v52, off
	v_cvt_f16_f32_e32 v56, v53
	v_add_co_u32_e32 v52, vcc, s62, v104
	v_mul_f32_e32 v60, v95, v111
	s_nop 0
	v_addc_co_u32_e32 v53, vcc, 0, v105, vcc
	global_store_short v[52:53], v56, off
	v_fma_mixlo_f16 v56, v90, v98, v99
	v_lshl_add_u64 v[52:53], v[102:103], 0, v[80:81]
	global_store_short v[52:53], v56, off
	v_add_co_u32_e32 v56, vcc, s55, v52
	v_mul_f32_e32 v61, v87, v60
	s_nop 0
	v_addc_co_u32_e32 v57, vcc, 0, v53, vcc
	global_store_short v[56:57], v64, off
	v_add_co_u32_e32 v56, vcc, s48, v52
	v_fma_mixlo_f16 v60, v87, v60, 0
	s_nop 0
	v_addc_co_u32_e32 v57, vcc, 0, v53, vcc
	global_store_short v[56:57], v60, off
	v_add_f32_e32 v56, v70, v118
	v_mul_f32_e32 v56, 0xbfb8aa3b, v56
	v_exp_f32_e32 v56, v56
	v_add_f32_e32 v57, v66, v120
	v_mul_f32_e32 v57, 0xbfb8aa3b, v57
	v_exp_f32_e32 v57, v57
	v_add_f32_e32 v56, 1.0, v56
	v_rcp_f32_e32 v56, v56
	v_add_f32_e32 v57, 1.0, v57
	v_rcp_f32_e32 v60, v57
	v_mul_f32_e32 v56, 0xbf1b4598, v56
	v_mul_f32_e32 v56, 0x3fb8aa3b, v56
	v_exp_f32_e32 v56, v56
	s_nop 0
	v_sub_f32_e32 v56, 1.0, v56
	v_cvt_f16_f32_e32 v64, v56
	v_add_co_u32_e32 v56, vcc, s49, v52
	s_nop 1
	v_addc_co_u32_e32 v57, vcc, 0, v53, vcc
	global_store_short v[56:57], v64, off
	v_add_co_u32_e32 v56, vcc, s60, v52
	v_fma_mixlo_f16 v64, v61, v60, 0
	s_nop 0
	v_addc_co_u32_e32 v57, vcc, 0, v53, vcc
	global_store_short v[56:57], v64, off
	v_add_f32_e32 v56, -1.0, v60
	v_fma_f32 v56, v117, v56, 1.0
	v_fma_mixlo_f16 v60, v95, v56, 0
	v_add_co_u32_e32 v56, vcc, s61, v52
	s_nop 1
	v_addc_co_u32_e32 v57, vcc, 0, v53, vcc
	global_store_short v[56:57], v60, off
	v_add_f32_e32 v56, v62, v119
	v_mul_f32_e32 v56, 0xbfb8aa3b, v56
	v_exp_f32_e32 v56, v56
	v_add_f32_e32 v57, v58, v121
	v_mul_f32_e32 v57, 0xbfb8aa3b, v57
	v_exp_f32_e32 v57, v57
	v_add_f32_e32 v56, 1.0, v56
	v_rcp_f32_e32 v56, v56
	v_add_f32_e32 v57, 1.0, v57
	v_rcp_f32_e32 v58, v57
	v_mul_f32_e32 v56, 0xbf1b4598, v56
	v_mul_f32_e32 v56, 0x3fb8aa3b, v56
	v_exp_f32_e32 v56, v56
	s_nop 0
	v_sub_f32_e32 v56, 1.0, v56
	v_cvt_f16_f32_e32 v60, v56
	v_add_co_u32_e32 v56, vcc, s3, v52
	s_nop 1
	v_addc_co_u32_e32 v57, vcc, 0, v53, vcc
	global_store_short v[56:57], v60, off
	v_add_co_u32_e32 v56, vcc, s74, v52
	v_fma_mixlo_f16 v60, v61, v58, 0
	s_nop 0
	v_addc_co_u32_e32 v57, vcc, 0, v53, vcc
	global_store_short v[56:57], v60, off
	v_add_f32_e32 v56, -1.0, v58
	v_fma_f32 v56, v117, v56, 1.0
	v_fma_mixlo_f16 v58, v95, v56, 0
	v_add_co_u32_e32 v56, vcc, s65, v52
	v_fma_mixlo_f16 v60, v94, v96, v97
	s_nop 0
	v_addc_co_u32_e32 v57, vcc, 0, v53, vcc
	v_add_co_u32_e32 v52, vcc, s62, v52
	global_store_short v[56:57], v58, off
	s_nop 0
	v_addc_co_u32_e32 v53, vcc, 0, v53, vcc
	global_store_short v[52:53], v54, off
	v_fma_mixlo_f16 v56, v90, v92, v93
	v_lshl_add_u64 v[52:53], v[102:103], 0, v[82:83]
	global_store_short v[52:53], v56, off
	v_add_co_u32_e32 v56, vcc, s55, v52
	v_mul_f32_e32 v54, v91, v111
	s_nop 0
	v_addc_co_u32_e32 v57, vcc, 0, v53, vcc
	global_store_short v[56:57], v60, off
	v_add_co_u32_e32 v56, vcc, s48, v52
	v_mul_f32_e32 v58, v86, v54
	v_fma_mixlo_f16 v54, v86, v54, 0
	v_addc_co_u32_e32 v57, vcc, 0, v53, vcc
	global_store_short v[56:57], v54, off
	v_add_f32_e32 v54, v71, v118
	v_mul_f32_e32 v54, 0xbfb8aa3b, v54
	v_exp_f32_e32 v54, v54
	v_add_f32_e32 v56, v67, v120
	v_mul_f32_e32 v56, 0xbfb8aa3b, v56
	v_exp_f32_e32 v56, v56
	v_add_f32_e32 v54, 1.0, v54
	v_rcp_f32_e32 v54, v54
	v_add_f32_e32 v56, 1.0, v56
	v_rcp_f32_e32 v60, v56
	v_mul_f32_e32 v54, 0xbf1b4598, v54
	v_mul_f32_e32 v54, 0x3fb8aa3b, v54
	v_exp_f32_e32 v54, v54
	v_add_co_u32_e32 v56, vcc, s49, v52
	v_sub_f32_e32 v54, 1.0, v54
	v_cvt_f16_f32_e32 v54, v54
	v_addc_co_u32_e32 v57, vcc, 0, v53, vcc
	global_store_short v[56:57], v54, off
	v_add_co_u32_e32 v56, vcc, s60, v52
	v_fma_mixlo_f16 v54, v58, v60, 0
	s_nop 0
	v_addc_co_u32_e32 v57, vcc, 0, v53, vcc
	global_store_short v[56:57], v54, off
	v_add_f32_e32 v54, -1.0, v60
	v_fma_f32 v54, v117, v54, 1.0
	v_add_co_u32_e32 v56, vcc, s61, v52
	v_fma_mixlo_f16 v54, v91, v54, 0
	s_nop 0
	v_addc_co_u32_e32 v57, vcc, 0, v53, vcc
	global_store_short v[56:57], v54, off
	v_add_f32_e32 v54, v63, v119
	v_mul_f32_e32 v54, 0xbfb8aa3b, v54
	v_exp_f32_e32 v54, v54
	v_add_f32_e32 v56, v59, v121
	v_mul_f32_e32 v56, 0xbfb8aa3b, v56
	v_exp_f32_e32 v56, v56
	v_add_f32_e32 v54, 1.0, v54
	v_rcp_f32_e32 v54, v54
	v_add_f32_e32 v56, 1.0, v56
	v_rcp_f32_e32 v59, v56
	v_mul_f32_e32 v54, 0xbf1b4598, v54
	v_mul_f32_e32 v54, 0x3fb8aa3b, v54
	v_exp_f32_e32 v54, v54
	v_add_co_u32_e32 v56, vcc, s3, v52
	v_sub_f32_e32 v54, 1.0, v54
	v_cvt_f16_f32_e32 v54, v54
	v_addc_co_u32_e32 v57, vcc, 0, v53, vcc
	global_store_short v[56:57], v54, off
	v_add_co_u32_e32 v56, vcc, s74, v52
	v_fma_mixlo_f16 v54, v58, v59, 0
	s_nop 0
	v_addc_co_u32_e32 v57, vcc, 0, v53, vcc
	global_store_short v[56:57], v54, off
	v_add_f32_e32 v54, -1.0, v59
	v_fma_f32 v54, v117, v54, 1.0
	v_add_co_u32_e32 v56, vcc, 0x8800000, v52
	v_fma_mixlo_f16 v54, v91, v54, 0
	s_nop 0
	v_addc_co_u32_e32 v57, vcc, 0, v53, vcc
	global_store_short v[56:57], v54, off
	v_cvt_f16_f32_e32 v54, v55
	v_add_co_u32_e32 v52, vcc, 0x9900000, v52
	s_nop 1
	v_addc_co_u32_e32 v53, vcc, 0, v53, vcc
	global_store_short v[52:53], v54, off
	s_cbranch_scc1 .LBB0_477
	s_add_i32 s4, s22, 0x100
	s_cmpk_gt_i32 s22, 0x33f
	s_mov_b32 s22, s4
	s_barrier
	s_cbranch_scc0 .LBB0_461
